# GEMM K-loops: counted lgkmcnt ladder in the MFMA segments - each MFMA waits only for the LDS fragments it reads instead of one lgkmcnt(0) per segment
# speedup vs baseline: 1.0064x; 1.0064x over previous
; #define PG8_STAGE(bufoff, gbase, voff) do { _Pragma("unroll") for (int _i = 0; _i < 2; ++_i) \
;         __builtin_amdgcn_global_load_lds((const unsigned*)((const char*)(gbase) + (voff)[_i]), (PG8_LAS unsigned*)(lds + (bufoff) + ldsw + _i * 8192), 16, 0, 0); } while (0)
; #define PG8_LDA(dst, b, h) do { _Pragma("unroll") for (int m = 0; m < 4; ++m) _Pragma("unroll") for (int k = 0; k < 2; ++k) dst[m][k] = *(const PG8_LAS bf16x8*)(lds + PG8_SA(b, h) + aoff + m * 2048 + k * 1024); } while (0)
; #define PG8_LDB(dst, b, h) do { _Pragma("unroll") for (int n = 0; n < 2; ++n) _Pragma("unroll") for (int k = 0; k < 2; ++k) dst[n][k] = *(const PG8_LAS bf16x8*)(lds + PG8_SB(b, h) + boff + n * 2048 + k * 1024); } while (0)
; #define PG8_MMA(ai, bj, At, Bt) do { __builtin_amdgcn_s_setprio(1); _Pragma("unroll") for (int m = 0; m < 4; ++m) _Pragma("unroll") for (int n = 0; n < 2; ++n) _Pragma("unroll") for (int k = 0; k < 2; ++k) \
;         acc[ai][bj][m][n] = __builtin_amdgcn_mfma_f32_16x16x32_bf16(Bt[n][k], At[m][k], acc[ai][bj][m][n], 0, 0, 0); __builtin_amdgcn_s_setprio(0); } while (0)
; #define PG8_WAIT_V(n) asm volatile("s_waitcnt vmcnt(" #n ")" ::: "memory")
; template <class Epi, class Sched>
; __device__ __forceinline__ void gemm_phase(PG8_LAS unsigned char* lds, const Gemm g, const Sched& S, const Epi& E) {
;     ...
;         for (int t = 0; t < nt; t += 2) {
;             const bool last = (t == nt - 2);
;             const char* a1 = cA + (size_t)(t + 1) * kstep;
;             const char* a2 = last ? nA : cA + (size_t)(t + 2) * kstep; const char* b2 = last ? nB : cB + (size_t)(t + 2) * kstep;
;             const char* a3 = a2 + kstep; const char* b3 = b2 + kstep;
;             if (last && has_next) S.a_ready(nxt);
;             PG8_LDB(B0, 0, 0); PG8_SCHED; PG8_LDA(At, 0, 0); PG8_STAGE(PG8_SA(1, 1), a1 + hstep, voffA);
;             PG8_WAIT_L(8); PG8_BAR; PG8_WAIT_L(0); PG8_MMA(0, 0, At, B0); PG8_BAR; PG8_SCHED;
;             PG8_LDB(B1, 0, 1); PG8_STAGE(PG8_SB(0, 0), b2, voffB);
;             PG8_BAR; PG8_WAIT_L(0); PG8_MMA(0, 1, At, B1); PG8_BAR;
;             PG8_LDA(At, 0, 1); PG8_STAGE(PG8_SA(0, 0), a2, voffA);
;             PG8_BAR; PG8_WAIT_L(0); PG8_MMA(1, 0, At, B0); PG8_BAR; PG8_SCHED;
;             PG8_STAGE(PG8_SB(0, 1), b2 + hstep, voffB);
;             PG8_WAIT_V(6); PG8_BAR; PG8_MMA(1, 1, At, B1); PG8_BAR;
.LBB0_96:
	s_add_u32 s10, s8, 0x100
	s_addc_u32 s11, s9, 0
	v_add_u32_e32 v154, 0x10000, v139
	ds_read_b128 v[142:145], v154
	ds_read_b128 v[146:149], v154 offset:1024
	ds_read_b128 v[150:153], v154 offset:2048
	ds_read_b128 v[154:157], v154 offset:3072
	s_cmp_eq_u32 s45, 40
	s_cselect_b32 s15, s1, s11
	s_cselect_b32 s14, s0, s10
	s_cselect_b32 s13, s5, s44
	s_cselect_b32 s12, s4, s43
	s_add_i32 m0, s20, 0xc000
	ds_read_b128 v[158:161], v141
	ds_read_b128 v[162:165], v141 offset:1024
	ds_read_b128 v[166:169], v141 offset:2048
	ds_read_b128 v[170:173], v141 offset:3072
	ds_read_b128 v[178:181], v141 offset:4096
	ds_read_b128 v[182:185], v141 offset:5120
	ds_read_b128 v[186:189], v141 offset:6144
	global_load_lds_dwordx4 v134, s[8:9]
	s_add_i32 m0, s20, 0xe000
	ds_read_b128 v[190:193], v141 offset:7168
	global_load_lds_dwordx4 v136, s[8:9]
	s_waitcnt lgkmcnt(8)
	s_barrier
	s_waitcnt lgkmcnt(7)
	v_mfma_f32_16x16x32_bf16 v[124:127], v[142:145], v[158:161], v[124:127]
	v_mfma_f32_16x16x32_bf16 v[120:123], v[150:153], v[158:161], v[120:123]
	s_waitcnt lgkmcnt(5)
	v_mfma_f32_16x16x32_bf16 v[116:119], v[142:145], v[166:169], v[116:119]
	v_mfma_f32_16x16x32_bf16 v[112:115], v[150:153], v[166:169], v[112:115]
	s_waitcnt lgkmcnt(3)
	v_mfma_f32_16x16x32_bf16 v[100:103], v[142:145], v[178:181], v[100:103]
	v_mfma_f32_16x16x32_bf16 v[96:99], v[150:153], v[178:181], v[96:99]
	s_waitcnt lgkmcnt(1)
	v_mfma_f32_16x16x32_bf16 v[84:87], v[142:145], v[186:189], v[84:87]
	v_mfma_f32_16x16x32_bf16 v[80:83], v[150:153], v[186:189], v[80:83]
	v_mfma_f32_16x16x32_bf16 v[124:127], v[146:149], v[162:165], v[124:127]
	v_mfma_f32_16x16x32_bf16 v[120:123], v[154:157], v[162:165], v[120:123]
	v_mfma_f32_16x16x32_bf16 v[116:119], v[146:149], v[170:173], v[116:119]
	v_mfma_f32_16x16x32_bf16 v[112:115], v[154:157], v[170:173], v[112:115]
	v_mfma_f32_16x16x32_bf16 v[100:103], v[146:149], v[182:185], v[100:103]
	v_mfma_f32_16x16x32_bf16 v[96:99], v[154:157], v[182:185], v[96:99]
	s_waitcnt lgkmcnt(0)
	v_mfma_f32_16x16x32_bf16 v[84:87], v[146:149], v[190:193], v[84:87]
	v_mfma_f32_16x16x32_bf16 v[80:83], v[154:157], v[190:193], v[80:83]
	s_barrier
	s_add_i32 s47, 0, 0x14000
	v_add_u32_e32 v174, 0x14000, v139
	ds_read_b128 v[194:197], v174
	ds_read_b128 v[198:201], v174 offset:1024
	s_add_u32 s98, s12, 0x80
	s_addc_u32 s99, s13, 0
	s_add_i32 m0, s18, 0x10000
	ds_read_b128 v[202:205], v174 offset:2048
	global_load_lds_dwordx4 v176, s[12:13]
	s_add_i32 m0, s18, 0x12000
	ds_read_b128 v[206:209], v174 offset:3072
	global_load_lds_dwordx4 v128, s[12:13]
	s_barrier
	s_waitcnt lgkmcnt(3)
	v_mfma_f32_16x16x32_bf16 v[108:111], v[194:197], v[158:161], v[108:111]
	s_waitcnt lgkmcnt(1)
	v_mfma_f32_16x16x32_bf16 v[104:107], v[202:205], v[158:161], v[104:107]
	v_mfma_f32_16x16x32_bf16 v[92:95], v[194:197], v[166:169], v[92:95]
	v_mfma_f32_16x16x32_bf16 v[88:91], v[202:205], v[166:169], v[88:91]
	v_mfma_f32_16x16x32_bf16 v[76:79], v[194:197], v[178:181], v[76:79]
	v_mfma_f32_16x16x32_bf16 v[72:75], v[202:205], v[178:181], v[72:75]
	v_mfma_f32_16x16x32_bf16 v[68:71], v[194:197], v[186:189], v[68:71]
	v_mfma_f32_16x16x32_bf16 v[64:67], v[202:205], v[186:189], v[64:67]
	v_mfma_f32_16x16x32_bf16 v[108:111], v[198:201], v[162:165], v[108:111]
	s_waitcnt lgkmcnt(0)
	v_mfma_f32_16x16x32_bf16 v[104:107], v[206:209], v[162:165], v[104:107]
	v_mfma_f32_16x16x32_bf16 v[92:95], v[198:201], v[170:173], v[92:95]
	v_mfma_f32_16x16x32_bf16 v[88:91], v[206:209], v[170:173], v[88:91]
	v_mfma_f32_16x16x32_bf16 v[76:79], v[198:201], v[182:185], v[76:79]
	v_mfma_f32_16x16x32_bf16 v[72:75], v[206:209], v[182:185], v[72:75]
	v_mfma_f32_16x16x32_bf16 v[68:71], v[198:201], v[190:193], v[68:71]
	v_mfma_f32_16x16x32_bf16 v[64:67], v[206:209], v[190:193], v[64:67]
	s_mov_b32 m0, s20
	s_add_u32 s100, s14, 0x80
	s_addc_u32 s101, s15, 0
	s_barrier
	ds_read_b128 v[158:161], v141 offset:16384
	ds_read_b128 v[162:165], v141 offset:17408
	ds_read_b128 v[166:169], v141 offset:18432
	ds_read_b128 v[170:173], v141 offset:19456
	ds_read_b128 v[178:181], v141 offset:20480
	ds_read_b128 v[182:185], v141 offset:21504
	ds_read_b128 v[186:189], v141 offset:22528
	global_load_lds_dwordx4 v132, s[14:15]
	s_mov_b32 m0, s21
	ds_read_b128 v[190:193], v141 offset:23552
	global_load_lds_dwordx4 v130, s[14:15]
	s_barrier
	s_waitcnt lgkmcnt(7)
	v_mfma_f32_16x16x32_bf16 v[60:63], v[142:145], v[158:161], v[60:63]
	v_mfma_f32_16x16x32_bf16 v[56:59], v[150:153], v[158:161], v[56:59]
	s_waitcnt lgkmcnt(5)
	v_mfma_f32_16x16x32_bf16 v[52:55], v[142:145], v[166:169], v[52:55]
	v_mfma_f32_16x16x32_bf16 v[48:51], v[150:153], v[166:169], v[48:51]
	s_waitcnt lgkmcnt(3)
	v_mfma_f32_16x16x32_bf16 v[36:39], v[142:145], v[178:181], v[36:39]
	v_mfma_f32_16x16x32_bf16 v[32:35], v[150:153], v[178:181], v[32:35]
	s_waitcnt lgkmcnt(1)
	v_mfma_f32_16x16x32_bf16 v[20:23], v[142:145], v[186:189], v[20:23]
	v_mfma_f32_16x16x32_bf16 v[16:19], v[150:153], v[186:189], v[16:19]
	v_mfma_f32_16x16x32_bf16 v[60:63], v[146:149], v[162:165], v[60:63]
	v_mfma_f32_16x16x32_bf16 v[56:59], v[154:157], v[162:165], v[56:59]
	v_mfma_f32_16x16x32_bf16 v[52:55], v[146:149], v[170:173], v[52:55]
	v_mfma_f32_16x16x32_bf16 v[48:51], v[154:157], v[170:173], v[48:51]
	v_mfma_f32_16x16x32_bf16 v[36:39], v[146:149], v[182:185], v[36:39]
	v_mfma_f32_16x16x32_bf16 v[32:35], v[154:157], v[182:185], v[32:35]
	s_waitcnt lgkmcnt(0)
	v_mfma_f32_16x16x32_bf16 v[20:23], v[146:149], v[190:193], v[20:23]
	v_mfma_f32_16x16x32_bf16 v[16:19], v[154:157], v[190:193], v[16:19]
	s_barrier
	s_add_u32 s8, s12, 0xb0000
	s_addc_u32 s9, s13, 0
	s_add_i32 m0, s18, 0x14000
	s_nop 0
	global_load_lds_dwordx4 v176, s[8:9]
	s_add_i32 m0, s18, 0x16000
	s_nop 0
	global_load_lds_dwordx4 v128, s[8:9]
	s_waitcnt vmcnt(6)
	s_barrier
; #define PG8_STAGE(bufoff, gbase, voff) do { _Pragma("unroll") for (int _i = 0; _i < 2; ++_i) \
;         __builtin_amdgcn_global_load_lds((const unsigned*)((const char*)(gbase) + (voff)[_i]), (PG8_LAS unsigned*)(lds + (bufoff) + ldsw + _i * 8192), 16, 0, 0); } while (0)
; #define PG8_LDA(dst, b, h) do { _Pragma("unroll") for (int m = 0; m < 4; ++m) _Pragma("unroll") for (int k = 0; k < 2; ++k) dst[m][k] = *(const PG8_LAS bf16x8*)(lds + PG8_SA(b, h) + aoff + m * 2048 + k * 1024); } while (0)
; #define PG8_LDB(dst, b, h) do { _Pragma("unroll") for (int n = 0; n < 2; ++n) _Pragma("unroll") for (int k = 0; k < 2; ++k) dst[n][k] = *(const PG8_LAS bf16x8*)(lds + PG8_SB(b, h) + boff + n * 2048 + k * 1024); } while (0)
; #define PG8_MMA(ai, bj, At, Bt) do { __builtin_amdgcn_s_setprio(1); _Pragma("unroll") for (int m = 0; m < 4; ++m) _Pragma("unroll") for (int n = 0; n < 2; ++n) _Pragma("unroll") for (int k = 0; k < 2; ++k) \
;         acc[ai][bj][m][n] = __builtin_amdgcn_mfma_f32_16x16x32_bf16(Bt[n][k], At[m][k], acc[ai][bj][m][n], 0, 0, 0); __builtin_amdgcn_s_setprio(0); } while (0)
; #define PG8_WAIT_V(n) asm volatile("s_waitcnt vmcnt(" #n ")" ::: "memory")
; #define PG8_WAIT_L(n) asm volatile("s_waitcnt lgkmcnt(" #n ")" ::: "memory")
; #define PG8_BAR __builtin_amdgcn_s_barrier()
; #define PG8_SCHED __builtin_amdgcn_sched_barrier(0)
; template <class Epi, class Sched>
; __device__ __forceinline__ void gemm_phase(PG8_LAS unsigned char* lds, const Gemm g, const Sched& S, const Epi& E) {
;     ...
;             PG8_WAIT_V(6); PG8_BAR; PG8_MMA(1, 1, At, B1); PG8_BAR;
;             PG8_LDB(B0, 1, 0); PG8_SCHED; PG8_LDA(At, 1, 0); PG8_STAGE(PG8_SA(0, 1), a2 + hstep, voffA);
;             PG8_WAIT_L(8); PG8_BAR; PG8_WAIT_L(0); PG8_MMA(0, 0, At, B0); PG8_BAR; PG8_SCHED;
;             PG8_LDB(B1, 1, 1); PG8_STAGE(PG8_SB(1, 0), b3, voffB);
;             PG8_BAR; PG8_WAIT_L(0); PG8_MMA(0, 1, At, B1); PG8_BAR;
;             PG8_LDA(At, 1, 1); PG8_STAGE(PG8_SA(1, 0), a3, voffA);
;             PG8_BAR; PG8_WAIT_L(0); PG8_MMA(1, 0, At, B0); PG8_BAR; PG8_SCHED;
	v_mfma_f32_16x16x32_bf16 v[44:47], v[194:197], v[158:161], v[44:47]
	v_mfma_f32_16x16x32_bf16 v[40:43], v[202:205], v[158:161], v[40:43]
	v_mfma_f32_16x16x32_bf16 v[28:31], v[194:197], v[166:169], v[28:31]
	v_mfma_f32_16x16x32_bf16 v[24:27], v[202:205], v[166:169], v[24:27]
	v_mfma_f32_16x16x32_bf16 v[12:15], v[194:197], v[178:181], v[12:15]
	v_mfma_f32_16x16x32_bf16 v[8:11], v[202:205], v[178:181], v[8:11]
	v_mfma_f32_16x16x32_bf16 v[4:7], v[194:197], v[186:189], v[4:7]
	v_mfma_f32_16x16x32_bf16 v[0:3], v[202:205], v[186:189], v[0:3]
	v_mfma_f32_16x16x32_bf16 v[44:47], v[198:201], v[162:165], v[44:47]
	v_mfma_f32_16x16x32_bf16 v[40:43], v[206:209], v[162:165], v[40:43]
	v_mfma_f32_16x16x32_bf16 v[28:31], v[198:201], v[170:173], v[28:31]
	v_mfma_f32_16x16x32_bf16 v[24:27], v[206:209], v[170:173], v[24:27]
	v_mfma_f32_16x16x32_bf16 v[12:15], v[198:201], v[182:185], v[12:15]
	v_mfma_f32_16x16x32_bf16 v[8:11], v[206:209], v[182:185], v[8:11]
	v_mfma_f32_16x16x32_bf16 v[4:7], v[198:201], v[190:193], v[4:7]
	v_mfma_f32_16x16x32_bf16 v[0:3], v[206:209], v[190:193], v[0:3]
	s_add_i32 s46, 0, 0x18000
	v_add_u32_e32 v154, 0x18000, v139
	s_barrier
	ds_read_b128 v[142:145], v154
	ds_read_b128 v[146:149], v154 offset:1024
	ds_read_b128 v[150:153], v154 offset:2048
	ds_read_b128 v[154:157], v154 offset:3072
	s_add_u32 s8, s14, 0xb0000
	s_addc_u32 s9, s15, 0
	s_mov_b32 m0, s22
	ds_read_b128 v[158:161], v141 offset:32768
	ds_read_b128 v[162:165], v141 offset:33792
	ds_read_b128 v[166:169], v141 offset:34816
	ds_read_b128 v[170:173], v141 offset:35840
	ds_read_b128 v[178:181], v141 offset:36864
	ds_read_b128 v[182:185], v141 offset:37888
	ds_read_b128 v[186:189], v141 offset:38912
	global_load_lds_dwordx4 v132, s[8:9]
	s_mov_b32 m0, s23
	ds_read_b128 v[190:193], v141 offset:39936
	global_load_lds_dwordx4 v130, s[8:9]
	s_waitcnt lgkmcnt(8)
	s_barrier
	s_waitcnt lgkmcnt(7)
	v_mfma_f32_16x16x32_bf16 v[124:127], v[142:145], v[158:161], v[124:127]
	v_mfma_f32_16x16x32_bf16 v[120:123], v[150:153], v[158:161], v[120:123]
	s_waitcnt lgkmcnt(5)
	v_mfma_f32_16x16x32_bf16 v[116:119], v[142:145], v[166:169], v[116:119]
	v_mfma_f32_16x16x32_bf16 v[112:115], v[150:153], v[166:169], v[112:115]
	s_waitcnt lgkmcnt(3)
	v_mfma_f32_16x16x32_bf16 v[100:103], v[142:145], v[178:181], v[100:103]
	v_mfma_f32_16x16x32_bf16 v[96:99], v[150:153], v[178:181], v[96:99]
	s_waitcnt lgkmcnt(1)
	v_mfma_f32_16x16x32_bf16 v[84:87], v[142:145], v[186:189], v[84:87]
	v_mfma_f32_16x16x32_bf16 v[80:83], v[150:153], v[186:189], v[80:83]
	v_mfma_f32_16x16x32_bf16 v[124:127], v[146:149], v[162:165], v[124:127]
	v_mfma_f32_16x16x32_bf16 v[120:123], v[154:157], v[162:165], v[120:123]
	v_mfma_f32_16x16x32_bf16 v[116:119], v[146:149], v[170:173], v[116:119]
	v_mfma_f32_16x16x32_bf16 v[112:115], v[154:157], v[170:173], v[112:115]
	v_mfma_f32_16x16x32_bf16 v[100:103], v[146:149], v[182:185], v[100:103]
	v_mfma_f32_16x16x32_bf16 v[96:99], v[154:157], v[182:185], v[96:99]
	s_waitcnt lgkmcnt(0)
	v_mfma_f32_16x16x32_bf16 v[84:87], v[146:149], v[190:193], v[84:87]
	v_mfma_f32_16x16x32_bf16 v[80:83], v[154:157], v[190:193], v[80:83]
	s_barrier
	v_add_u32_e32 v206, 0x1c000, v139
	s_add_i32 m0, s18, 0x18000
	ds_read_b128 v[194:197], v206
	ds_read_b128 v[198:201], v206 offset:1024
	ds_read_b128 v[202:205], v206 offset:2048
	global_load_lds_dwordx4 v176, s[98:99]
	s_add_i32 m0, s18, 0x1a000
	ds_read_b128 v[206:209], v206 offset:3072
	global_load_lds_dwordx4 v128, s[98:99]
	s_barrier
	s_waitcnt lgkmcnt(3)
	v_mfma_f32_16x16x32_bf16 v[108:111], v[194:197], v[158:161], v[108:111]
	s_waitcnt lgkmcnt(1)
	v_mfma_f32_16x16x32_bf16 v[104:107], v[202:205], v[158:161], v[104:107]
	v_mfma_f32_16x16x32_bf16 v[92:95], v[194:197], v[166:169], v[92:95]
	v_mfma_f32_16x16x32_bf16 v[88:91], v[202:205], v[166:169], v[88:91]
	v_mfma_f32_16x16x32_bf16 v[76:79], v[194:197], v[178:181], v[76:79]
	v_mfma_f32_16x16x32_bf16 v[72:75], v[202:205], v[178:181], v[72:75]
	v_mfma_f32_16x16x32_bf16 v[68:71], v[194:197], v[186:189], v[68:71]
	v_mfma_f32_16x16x32_bf16 v[64:67], v[202:205], v[186:189], v[64:67]
	v_mfma_f32_16x16x32_bf16 v[108:111], v[198:201], v[162:165], v[108:111]
	s_waitcnt lgkmcnt(0)
	v_mfma_f32_16x16x32_bf16 v[104:107], v[206:209], v[162:165], v[104:107]
	v_mfma_f32_16x16x32_bf16 v[92:95], v[198:201], v[170:173], v[92:95]
	v_mfma_f32_16x16x32_bf16 v[88:91], v[206:209], v[170:173], v[88:91]
	v_mfma_f32_16x16x32_bf16 v[76:79], v[198:201], v[182:185], v[76:79]
	v_mfma_f32_16x16x32_bf16 v[72:75], v[206:209], v[182:185], v[72:75]
	v_mfma_f32_16x16x32_bf16 v[68:71], v[198:201], v[190:193], v[68:71]
	v_mfma_f32_16x16x32_bf16 v[64:67], v[206:209], v[190:193], v[64:67]
	s_mov_b32 m0, s27
	s_barrier
	ds_read_b128 v[158:161], v141 offset:49152
	ds_read_b128 v[162:165], v141 offset:50176
	ds_read_b128 v[166:169], v141 offset:51200
	ds_read_b128 v[170:173], v141 offset:52224
	ds_read_b128 v[178:181], v141 offset:53248
	ds_read_b128 v[182:185], v141 offset:54272
	ds_read_b128 v[186:189], v141 offset:55296
	global_load_lds_dwordx4 v132, s[100:101]
	s_mov_b32 m0, s28
	ds_read_b128 v[190:193], v141 offset:56320
	global_load_lds_dwordx4 v130, s[100:101]
	s_barrier
; #define PG8_STAGE(bufoff, gbase, voff) do { _Pragma("unroll") for (int _i = 0; _i < 2; ++_i) \
;         __builtin_amdgcn_global_load_lds((const unsigned*)((const char*)(gbase) + (voff)[_i]), (PG8_LAS unsigned*)(lds + (bufoff) + ldsw + _i * 8192), 16, 0, 0); } while (0)
; #define PG8_MMA(ai, bj, At, Bt) do { __builtin_amdgcn_s_setprio(1); _Pragma("unroll") for (int m = 0; m < 4; ++m) _Pragma("unroll") for (int n = 0; n < 2; ++n) _Pragma("unroll") for (int k = 0; k < 2; ++k) \
;         acc[ai][bj][m][n] = __builtin_amdgcn_mfma_f32_16x16x32_bf16(Bt[n][k], At[m][k], acc[ai][bj][m][n], 0, 0, 0); __builtin_amdgcn_s_setprio(0); } while (0)
; #define PG8_WAIT_V(n) asm volatile("s_waitcnt vmcnt(" #n ")" ::: "memory")
; #define PG8_WAIT_L(n) asm volatile("s_waitcnt lgkmcnt(" #n ")" ::: "memory")
; #define PG8_BAR __builtin_amdgcn_s_barrier()
; #define PG8_SCHED __builtin_amdgcn_sched_barrier(0)
; template <class Epi, class Sched>
; __device__ __forceinline__ void gemm_phase(PG8_LAS unsigned char* lds, const Gemm g, const Sched& S, const Epi& E) {
;     ...
;             PG8_BAR; PG8_WAIT_L(0); PG8_MMA(1, 0, At, B0); PG8_BAR; PG8_SCHED;
;             PG8_STAGE(PG8_SB(1, 1), b3 + hstep, voffB);
;             PG8_WAIT_V(6); PG8_BAR; PG8_MMA(1, 1, At, B1); PG8_BAR;
;         }
	s_waitcnt lgkmcnt(7)
	v_mfma_f32_16x16x32_bf16 v[60:63], v[142:145], v[158:161], v[60:63]
	v_mfma_f32_16x16x32_bf16 v[56:59], v[150:153], v[158:161], v[56:59]
	s_waitcnt lgkmcnt(5)
	v_mfma_f32_16x16x32_bf16 v[52:55], v[142:145], v[166:169], v[52:55]
	v_mfma_f32_16x16x32_bf16 v[48:51], v[150:153], v[166:169], v[48:51]
	s_waitcnt lgkmcnt(3)
	v_mfma_f32_16x16x32_bf16 v[36:39], v[142:145], v[178:181], v[36:39]
	v_mfma_f32_16x16x32_bf16 v[32:35], v[150:153], v[178:181], v[32:35]
	s_waitcnt lgkmcnt(1)
	v_mfma_f32_16x16x32_bf16 v[20:23], v[142:145], v[186:189], v[20:23]
	v_mfma_f32_16x16x32_bf16 v[16:19], v[150:153], v[186:189], v[16:19]
	v_mfma_f32_16x16x32_bf16 v[60:63], v[146:149], v[162:165], v[60:63]
	v_mfma_f32_16x16x32_bf16 v[56:59], v[154:157], v[162:165], v[56:59]
	v_mfma_f32_16x16x32_bf16 v[52:55], v[146:149], v[170:173], v[52:55]
	v_mfma_f32_16x16x32_bf16 v[48:51], v[154:157], v[170:173], v[48:51]
	v_mfma_f32_16x16x32_bf16 v[36:39], v[146:149], v[182:185], v[36:39]
	v_mfma_f32_16x16x32_bf16 v[32:35], v[154:157], v[182:185], v[32:35]
	s_waitcnt lgkmcnt(0)
	v_mfma_f32_16x16x32_bf16 v[20:23], v[146:149], v[190:193], v[20:23]
	v_mfma_f32_16x16x32_bf16 v[16:19], v[154:157], v[190:193], v[16:19]
	s_barrier
	s_add_u32 s8, s12, 0xb0080
	s_addc_u32 s9, s13, 0
	s_add_i32 m0, s18, 0x1c000
	s_nop 0
	global_load_lds_dwordx4 v176, s[8:9]
	s_add_i32 m0, s18, 0x1e000
	s_nop 0
	global_load_lds_dwordx4 v128, s[8:9]
	s_waitcnt vmcnt(6)
	s_barrier
	v_mfma_f32_16x16x32_bf16 v[44:47], v[194:197], v[158:161], v[44:47]
	v_mfma_f32_16x16x32_bf16 v[40:43], v[202:205], v[158:161], v[40:43]
	v_mfma_f32_16x16x32_bf16 v[28:31], v[194:197], v[166:169], v[28:31]
	v_mfma_f32_16x16x32_bf16 v[24:27], v[202:205], v[166:169], v[24:27]
	v_mfma_f32_16x16x32_bf16 v[12:15], v[194:197], v[178:181], v[12:15]
	v_mfma_f32_16x16x32_bf16 v[8:11], v[202:205], v[178:181], v[8:11]
	v_mfma_f32_16x16x32_bf16 v[4:7], v[194:197], v[186:189], v[4:7]
	v_mfma_f32_16x16x32_bf16 v[0:3], v[202:205], v[186:189], v[0:3]
	v_mfma_f32_16x16x32_bf16 v[44:47], v[198:201], v[162:165], v[44:47]
	v_mfma_f32_16x16x32_bf16 v[40:43], v[206:209], v[162:165], v[40:43]
	v_mfma_f32_16x16x32_bf16 v[28:31], v[198:201], v[170:173], v[28:31]
	v_mfma_f32_16x16x32_bf16 v[24:27], v[206:209], v[170:173], v[24:27]
	v_mfma_f32_16x16x32_bf16 v[12:15], v[198:201], v[182:185], v[12:15]
	v_mfma_f32_16x16x32_bf16 v[8:11], v[206:209], v[182:185], v[8:11]
	v_mfma_f32_16x16x32_bf16 v[4:7], v[198:201], v[190:193], v[4:7]
	v_mfma_f32_16x16x32_bf16 v[0:3], v[206:209], v[190:193], v[0:3]
	s_add_i32 s45, s45, 2
	s_add_u32 s43, s43, 0x100
	s_addc_u32 s44, s44, 0
	s_cmp_gt_u32 s45, 41
	s_mov_b64 s[8:9], s[10:11]
	s_barrier
	s_cbranch_scc0 .LBB0_96
; __device__ __forceinline__ unsigned cvtpk(float lo, float hi) { const f32x2 v = (f32x2){lo, hi}; const bf16v2 b = __builtin_convertvector(v, bf16v2); return __builtin_bit_cast(unsigned, b); }
; template <class Epi, class Sched>
; __device__ __forceinline__ void gemm_phase(PG8_LAS unsigned char* lds, const Gemm g, const Sched& S, const Epi& E) {
;     ...
;         if constexpr (!Epi::AFTER_DRAIN) { E(acc, cur, wr, wc, fr, fq); S.done(cur); }
;         if (!has_next) break;
; #pragma unroll
;         for (int a = 0; a < 2; ++a)
; #pragma unroll
;             for (int b = 0; b < 2; ++b)
; #pragma unroll
;                 for (int m = 0; m < 4; ++m)
; #pragma unroll
;                     for (int n = 0; n < 2; ++n) acc[a][b][m][n] = (f32x4){0.f, 0.f, 0.f, 0.f};
;         cur = nxt; cA = nA; cB = nB; ++ui;
;     __device__ __forceinline__ void operator()(const f32x4 (&acc)[2][2][4][2], const pg8::Unit& u, int wr, int wc, int fr, int fq) const {
;         const int row0 = u.pm * 256 + wr * 64 + fr, col0 = u.pn * 256 + wc * 32 + 8 * fq;
; #pragma unroll
;         for (int ai = 0; ai < 2; ++ai)
; #pragma unroll
;             for (int m = 0; m < 4; ++m) { bf16_t* rowp = O + (size_t)(row0 + ai * 128 + m * 16) * ldc + col0;
; #pragma unroll
;                 for (int bj = 0; bj < 2; ++bj) { const f32x4 v0 = acc[ai][bj][m][0], v1 = acc[ai][bj][m][1];
;                     u32x4 w; w.x = cvtpk(v0[0], v0[1]); w.y = cvtpk(v0[2], v0[3]); w.z = cvtpk(v1[0], v1[1]); w.w = cvtpk(v1[2], v1[3]);
;                     *(u32x4*)(rowp + bj * 128) = w; } }
;     }
	v_lshl_add_u32 v142, s29, 8, v138
	v_lshl_or_b32 v144, s34, 8, v140
	v_ashrrev_i32_e32 v143, 31, v142
	v_readlane_b32 s8, v253, 18
	v_cvt_pk_bf16_f32 v108, v108, v109
	v_cvt_pk_bf16_f32 v109, v110, v111
	v_cvt_pk_bf16_f32 v110, v104, v105
	v_or_b32_e32 v104, 16, v142
	v_cvt_pk_bf16_f32 v92, v92, v93
	v_cvt_pk_bf16_f32 v93, v94, v95
	v_cvt_pk_bf16_f32 v94, v88, v89
	v_or_b32_e32 v88, 32, v142
	v_cvt_pk_bf16_f32 v76, v76, v77
	v_cvt_pk_bf16_f32 v77, v78, v79
	v_cvt_pk_bf16_f32 v78, v72, v73
	v_or_b32_e32 v72, 48, v142
	v_ashrrev_i32_e32 v145, 31, v144
	v_lshlrev_b64 v[146:147], 11, v[142:143]
	v_readlane_b32 s9, v253, 19
	v_ashrrev_i32_e32 v105, 31, v104
	v_ashrrev_i32_e32 v89, 31, v88
	v_ashrrev_i32_e32 v73, 31, v72
	v_lshl_add_u64 v[146:147], s[8:9], 0, v[146:147]
	v_lshlrev_b64 v[144:145], 1, v[144:145]
	v_lshlrev_b64 v[104:105], 11, v[104:105]
	v_lshlrev_b64 v[88:89], 11, v[88:89]
	v_lshlrev_b64 v[72:73], 11, v[72:73]
	v_lshl_add_u64 v[146:147], v[146:147], 0, v[144:145]
	v_lshl_add_u64 v[104:105], s[8:9], 0, v[104:105]
	v_lshl_add_u64 v[88:89], s[8:9], 0, v[88:89]
	v_lshl_add_u64 v[72:73], s[8:9], 0, v[72:73]
	s_mov_b64 s[8:9], 0x40000
	v_cvt_pk_bf16_f32 v68, v68, v69
	v_cvt_pk_bf16_f32 v69, v70, v71
	v_cvt_pk_bf16_f32 v70, v64, v65
	v_lshl_add_u64 v[64:65], v[146:147], 0, s[8:9]
	v_cvt_pk_bf16_f32 v60, v60, v61
	v_cvt_pk_bf16_f32 v61, v62, v63
	v_cvt_pk_bf16_f32 v62, v56, v57
	v_add_co_u32_e32 v56, vcc, s2, v146
	v_cvt_pk_bf16_f32 v44, v44, v45
	v_cvt_pk_bf16_f32 v45, v46, v47
	v_cvt_pk_bf16_f32 v46, v40, v41
	v_cvt_pk_bf16_f32 v47, v42, v43
	s_mov_b64 s[8:9], 0x48000
	v_addc_co_u32_e32 v57, vcc, 0, v147, vcc
	global_store_dwordx4 v[64:65], v[44:47], off offset:256
	v_cvt_pk_bf16_f32 v28, v28, v29
	v_cvt_pk_bf16_f32 v29, v30, v31
	v_lshl_add_u64 v[44:45], v[146:147], 0, s[8:9]
	s_mov_b32 s8, 0x48000
	v_add_co_u32_e32 v46, vcc, s8, v146
	v_cvt_pk_bf16_f32 v30, v24, v25
	v_cvt_pk_bf16_f32 v31, v26, v27
	s_mov_b64 s[8:9], 0x50000
	v_addc_co_u32_e32 v47, vcc, 0, v147, vcc
	global_store_dwordx4 v[44:45], v[28:31], off offset:256
	v_cvt_pk_bf16_f32 v12, v12, v13
	v_cvt_pk_bf16_f32 v13, v14, v15
	v_lshl_add_u64 v[28:29], v[146:147], 0, s[8:9]
	s_mov_b32 s8, 0x50000
	v_add_co_u32_e32 v30, vcc, s8, v146
	v_cvt_pk_bf16_f32 v14, v8, v9
	v_cvt_pk_bf16_f32 v15, v10, v11
	s_mov_b64 s[8:9], 0x58000
	v_cvt_pk_bf16_f32 v111, v106, v107
	v_addc_co_u32_e32 v31, vcc, 0, v147, vcc
	global_store_dwordx4 v[28:29], v[12:15], off offset:256
	global_store_dwordx4 v[146:147], v[108:111], off offset:256
	v_cvt_pk_bf16_f32 v95, v90, v91
	v_lshl_add_u64 v[12:13], v[146:147], 0, s[8:9]
	s_mov_b32 s8, 0x58000
	v_lshl_add_u64 v[108:109], v[104:105], 0, v[144:145]
	v_add_co_u32_e32 v14, vcc, s8, v146
	global_store_dwordx4 v[108:109], v[92:95], off offset:256
	v_cvt_pk_bf16_f32 v79, v74, v75
	v_addc_co_u32_e32 v15, vcc, 0, v147, vcc
	v_lshl_add_u64 v[92:93], v[88:89], 0, v[144:145]
	v_cvt_pk_bf16_f32 v124, v124, v125
	v_cvt_pk_bf16_f32 v125, v126, v127
	v_cvt_pk_bf16_f32 v126, v120, v121
	v_cvt_pk_bf16_f32 v127, v122, v123
	v_cvt_pk_bf16_f32 v104, v116, v117
	v_cvt_pk_bf16_f32 v105, v118, v119
	v_cvt_pk_bf16_f32 v106, v112, v113
	v_cvt_pk_bf16_f32 v107, v114, v115
	v_cvt_pk_bf16_f32 v88, v100, v101
	v_cvt_pk_bf16_f32 v89, v102, v103
	v_cvt_pk_bf16_f32 v90, v96, v97
	v_cvt_pk_bf16_f32 v91, v98, v99
	global_store_dwordx4 v[92:93], v[76:79], off offset:256
	v_cvt_pk_bf16_f32 v74, v80, v81
	v_cvt_pk_bf16_f32 v75, v82, v83
	v_lshl_add_u64 v[76:77], v[72:73], 0, v[144:145]
	v_cvt_pk_bf16_f32 v72, v84, v85
	v_cvt_pk_bf16_f32 v73, v86, v87
	v_cvt_pk_bf16_f32 v71, v66, v67
	v_cvt_pk_bf16_f32 v63, v58, v59
	v_cvt_pk_bf16_f32 v40, v52, v53
	v_cvt_pk_bf16_f32 v41, v54, v55
	v_cvt_pk_bf16_f32 v42, v48, v49
	v_cvt_pk_bf16_f32 v43, v50, v51
	v_cvt_pk_bf16_f32 v24, v36, v37
	v_cvt_pk_bf16_f32 v25, v38, v39
	v_cvt_pk_bf16_f32 v26, v32, v33
	v_cvt_pk_bf16_f32 v27, v34, v35
	v_cvt_pk_bf16_f32 v8, v20, v21
	v_cvt_pk_bf16_f32 v9, v22, v23
	v_cvt_pk_bf16_f32 v10, v16, v17
	v_cvt_pk_bf16_f32 v11, v18, v19
	v_cvt_pk_bf16_f32 v4, v4, v5
	v_cvt_pk_bf16_f32 v5, v6, v7
	v_cvt_pk_bf16_f32 v6, v0, v1
	v_cvt_pk_bf16_f32 v7, v2, v3
	s_and_b64 vcc, exec, s[38:39]
	s_mov_b32 s34, s40
	s_mov_b32 s29, s41
	s_mov_b64 s[10:11], s[4:5]
	s_mov_b64 s[8:9], s[0:1]
	global_store_dwordx4 v[146:147], v[124:127], off
	global_store_dwordx4 v[108:109], v[104:107], off
	global_store_dwordx4 v[92:93], v[88:91], off
	global_store_dwordx4 v[76:77], v[72:75], off
	global_store_dwordx4 v[76:77], v[68:71], off offset:256
	global_store_dwordx4 v[56:57], v[60:63], off
	global_store_dwordx4 v[46:47], v[40:43], off
	global_store_dwordx4 v[30:31], v[24:27], off
	global_store_dwordx4 v[14:15], v[8:11], off
	global_store_dwordx4 v[12:13], v[4:7], off offset:256
	s_cbranch_vccz .LBB0_89
	s_waitcnt vmcnt(0)
	s_cmpk_gt_u32 s17, 0xff
	v_readlane_b32 s2, v254, 59
	s_cbranch_scc1 .LBB0_100
	s_barrier

; #define PG8_STAGE(bufoff, gbase, voff) do { _Pragma("unroll") for (int _i = 0; _i < 2; ++_i) \
;         __builtin_amdgcn_global_load_lds((const unsigned*)((const char*)(gbase) + (voff)[_i]), (PG8_LAS unsigned*)(lds + (bufoff) + ldsw + _i * 8192), 16, 0, 0); } while (0)
; #define PG8_LDA(dst, b, h) do { _Pragma("unroll") for (int m = 0; m < 4; ++m) _Pragma("unroll") for (int k = 0; k < 2; ++k) dst[m][k] = *(const PG8_LAS bf16x8*)(lds + PG8_SA(b, h) + aoff + m * 2048 + k * 1024); } while (0)
; #define PG8_LDB(dst, b, h) do { _Pragma("unroll") for (int n = 0; n < 2; ++n) _Pragma("unroll") for (int k = 0; k < 2; ++k) dst[n][k] = *(const PG8_LAS bf16x8*)(lds + PG8_SB(b, h) + boff + n * 2048 + k * 1024); } while (0)
; #define PG8_MMA(ai, bj, At, Bt) do { __builtin_amdgcn_s_setprio(1); _Pragma("unroll") for (int m = 0; m < 4; ++m) _Pragma("unroll") for (int n = 0; n < 2; ++n) _Pragma("unroll") for (int k = 0; k < 2; ++k) \
;         acc[ai][bj][m][n] = __builtin_amdgcn_mfma_f32_16x16x32_bf16(Bt[n][k], At[m][k], acc[ai][bj][m][n], 0, 0, 0); __builtin_amdgcn_s_setprio(0); } while (0)
; #define PG8_WAIT_L(n) asm volatile("s_waitcnt lgkmcnt(" #n ")" ::: "memory")
; #define PG8_BAR __builtin_amdgcn_s_barrier()
; #define PG8_SCHED __builtin_amdgcn_sched_barrier(0)
; template <class Epi, class Sched>
; __device__ __forceinline__ void gemm_phase(PG8_LAS unsigned char* lds, const Gemm g, const Sched& S, const Epi& E) {
;     ...
;         for (int t = 0; t < nt; t += 2) {
;             const bool last = (t == nt - 2);
;             const char* a1 = cA + (size_t)(t + 1) * kstep;
;             const char* a2 = last ? nA : cA + (size_t)(t + 2) * kstep; const char* b2 = last ? nB : cB + (size_t)(t + 2) * kstep;
;             const char* a3 = a2 + kstep; const char* b3 = b2 + kstep;
;             if (last && has_next) S.a_ready(nxt);
;             PG8_LDB(B0, 0, 0); PG8_SCHED; PG8_LDA(At, 0, 0); PG8_STAGE(PG8_SA(1, 1), a1 + hstep, voffA);
;             PG8_WAIT_L(8); PG8_BAR; PG8_WAIT_L(0); PG8_MMA(0, 0, At, B0); PG8_BAR; PG8_SCHED;
;             PG8_LDB(B1, 0, 1); PG8_STAGE(PG8_SB(0, 0), b2, voffB);
;             PG8_BAR; PG8_WAIT_L(0); PG8_MMA(0, 1, At, B1); PG8_BAR;
;             PG8_LDA(At, 0, 1); PG8_STAGE(PG8_SA(0, 0), a2, voffA);
;             PG8_BAR; PG8_WAIT_L(0); PG8_MMA(1, 0, At, B0); PG8_BAR; PG8_SCHED;
.LBB0_114:
	s_add_u32 s14, s12, 0xfffc0080
	s_addc_u32 s15, s13, -1
	v_add_u32_e32 v154, 0x10000, v143
	ds_read_b128 v[138:141], v154
	ds_read_b128 v[146:149], v154 offset:1024
	ds_read_b128 v[150:153], v154 offset:2048
	ds_read_b128 v[154:157], v154 offset:3072
	s_cmp_eq_u32 s45, 12
	s_cselect_b32 s17, s5, s15
	s_cselect_b32 s16, s40, s14
	s_cselect_b32 s15, s1, s44
	s_cselect_b32 s14, s41, s43
	s_add_i32 m0, s11, 0xc000
	ds_read_b128 v[158:161], v145
	ds_read_b128 v[162:165], v145 offset:1024
	ds_read_b128 v[166:169], v145 offset:2048
	ds_read_b128 v[170:173], v145 offset:3072
	ds_read_b128 v[178:181], v145 offset:4096
	ds_read_b128 v[182:185], v145 offset:5120
	ds_read_b128 v[186:189], v145 offset:6144
	global_load_lds_dwordx4 v134, s[12:13]
	s_add_i32 m0, s11, 0xe000
	ds_read_b128 v[190:193], v145 offset:7168
	global_load_lds_dwordx4 v136, s[12:13]
	s_waitcnt lgkmcnt(8)
	s_barrier
	s_waitcnt lgkmcnt(7)
	v_mfma_f32_16x16x32_bf16 v[124:127], v[138:141], v[158:161], v[124:127]
	v_mfma_f32_16x16x32_bf16 v[116:119], v[150:153], v[158:161], v[116:119]
	s_waitcnt lgkmcnt(5)
	v_mfma_f32_16x16x32_bf16 v[108:111], v[138:141], v[166:169], v[108:111]
	v_mfma_f32_16x16x32_bf16 v[100:103], v[150:153], v[166:169], v[100:103]
	s_waitcnt lgkmcnt(3)
	v_mfma_f32_16x16x32_bf16 v[92:95], v[138:141], v[178:181], v[92:95]
	v_mfma_f32_16x16x32_bf16 v[84:87], v[150:153], v[178:181], v[84:87]
	s_waitcnt lgkmcnt(1)
	v_mfma_f32_16x16x32_bf16 v[76:79], v[138:141], v[186:189], v[76:79]
	v_mfma_f32_16x16x32_bf16 v[68:71], v[150:153], v[186:189], v[68:71]
	v_mfma_f32_16x16x32_bf16 v[124:127], v[146:149], v[162:165], v[124:127]
	v_mfma_f32_16x16x32_bf16 v[116:119], v[154:157], v[162:165], v[116:119]
	v_mfma_f32_16x16x32_bf16 v[108:111], v[146:149], v[170:173], v[108:111]
	v_mfma_f32_16x16x32_bf16 v[100:103], v[154:157], v[170:173], v[100:103]
	v_mfma_f32_16x16x32_bf16 v[92:95], v[146:149], v[182:185], v[92:95]
	v_mfma_f32_16x16x32_bf16 v[84:87], v[154:157], v[182:185], v[84:87]
	s_waitcnt lgkmcnt(0)
	v_mfma_f32_16x16x32_bf16 v[76:79], v[146:149], v[190:193], v[76:79]
	v_mfma_f32_16x16x32_bf16 v[68:71], v[154:157], v[190:193], v[68:71]
	s_barrier
	s_add_i32 s48, 0, 0x14000
	v_add_u32_e32 v174, 0x14000, v143
	ds_read_b128 v[194:197], v174
	ds_read_b128 v[198:201], v174 offset:1024
	s_add_u32 s98, s14, 0x80
	s_addc_u32 s99, s15, 0
	s_add_i32 m0, s20, 0x10000
	ds_read_b128 v[202:205], v174 offset:2048
	global_load_lds_dwordx4 v176, s[14:15]
	s_add_i32 m0, s20, 0x12000
	ds_read_b128 v[206:209], v174 offset:3072
	global_load_lds_dwordx4 v128, s[14:15]
	s_barrier
	s_waitcnt lgkmcnt(3)
	v_mfma_f32_16x16x32_bf16 v[120:123], v[194:197], v[158:161], v[120:123]
	s_waitcnt lgkmcnt(1)
	v_mfma_f32_16x16x32_bf16 v[112:115], v[202:205], v[158:161], v[112:115]
	v_mfma_f32_16x16x32_bf16 v[104:107], v[194:197], v[166:169], v[104:107]
	v_mfma_f32_16x16x32_bf16 v[96:99], v[202:205], v[166:169], v[96:99]
	v_mfma_f32_16x16x32_bf16 v[88:91], v[194:197], v[178:181], v[88:91]
	v_mfma_f32_16x16x32_bf16 v[80:83], v[202:205], v[178:181], v[80:83]
	v_mfma_f32_16x16x32_bf16 v[72:75], v[194:197], v[186:189], v[72:75]
	v_mfma_f32_16x16x32_bf16 v[64:67], v[202:205], v[186:189], v[64:67]
	v_mfma_f32_16x16x32_bf16 v[120:123], v[198:201], v[162:165], v[120:123]
	s_waitcnt lgkmcnt(0)
	v_mfma_f32_16x16x32_bf16 v[112:115], v[206:209], v[162:165], v[112:115]
	v_mfma_f32_16x16x32_bf16 v[104:107], v[198:201], v[170:173], v[104:107]
	v_mfma_f32_16x16x32_bf16 v[96:99], v[206:209], v[170:173], v[96:99]
	v_mfma_f32_16x16x32_bf16 v[88:91], v[198:201], v[182:185], v[88:91]
	v_mfma_f32_16x16x32_bf16 v[80:83], v[206:209], v[182:185], v[80:83]
	v_mfma_f32_16x16x32_bf16 v[72:75], v[198:201], v[190:193], v[72:75]
	v_mfma_f32_16x16x32_bf16 v[64:67], v[206:209], v[190:193], v[64:67]
	s_mov_b32 m0, s11
	s_add_u32 s100, s16, 0x80
	s_addc_u32 s101, s17, 0
	s_barrier
	ds_read_b128 v[158:161], v145 offset:16384
	ds_read_b128 v[162:165], v145 offset:17408
	ds_read_b128 v[166:169], v145 offset:18432
	ds_read_b128 v[170:173], v145 offset:19456
	ds_read_b128 v[178:181], v145 offset:20480
	ds_read_b128 v[182:185], v145 offset:21504
	ds_read_b128 v[186:189], v145 offset:22528
	global_load_lds_dwordx4 v132, s[16:17]
	s_mov_b32 m0, s22
	ds_read_b128 v[190:193], v145 offset:23552
	global_load_lds_dwordx4 v130, s[16:17]
	s_barrier
	s_waitcnt lgkmcnt(7)
	v_mfma_f32_16x16x32_bf16 v[60:63], v[138:141], v[158:161], v[60:63]
	v_mfma_f32_16x16x32_bf16 v[52:55], v[150:153], v[158:161], v[52:55]
	s_waitcnt lgkmcnt(5)
	v_mfma_f32_16x16x32_bf16 v[44:47], v[138:141], v[166:169], v[44:47]
	v_mfma_f32_16x16x32_bf16 v[36:39], v[150:153], v[166:169], v[36:39]
	s_waitcnt lgkmcnt(3)
	v_mfma_f32_16x16x32_bf16 v[28:31], v[138:141], v[178:181], v[28:31]
	v_mfma_f32_16x16x32_bf16 v[20:23], v[150:153], v[178:181], v[20:23]
	s_waitcnt lgkmcnt(1)
	v_mfma_f32_16x16x32_bf16 v[12:15], v[138:141], v[186:189], v[12:15]
	v_mfma_f32_16x16x32_bf16 v[4:7], v[150:153], v[186:189], v[4:7]
	v_mfma_f32_16x16x32_bf16 v[60:63], v[146:149], v[162:165], v[60:63]
	v_mfma_f32_16x16x32_bf16 v[52:55], v[154:157], v[162:165], v[52:55]
	v_mfma_f32_16x16x32_bf16 v[44:47], v[146:149], v[170:173], v[44:47]
	v_mfma_f32_16x16x32_bf16 v[36:39], v[154:157], v[170:173], v[36:39]
	v_mfma_f32_16x16x32_bf16 v[28:31], v[146:149], v[182:185], v[28:31]
	v_mfma_f32_16x16x32_bf16 v[20:23], v[154:157], v[182:185], v[20:23]
	s_waitcnt lgkmcnt(0)
	v_mfma_f32_16x16x32_bf16 v[12:15], v[146:149], v[190:193], v[12:15]
	v_mfma_f32_16x16x32_bf16 v[4:7], v[154:157], v[190:193], v[4:7]
	s_barrier
; #define PG8_STAGE(bufoff, gbase, voff) do { _Pragma("unroll") for (int _i = 0; _i < 2; ++_i) \
;         __builtin_amdgcn_global_load_lds((const unsigned*)((const char*)(gbase) + (voff)[_i]), (PG8_LAS unsigned*)(lds + (bufoff) + ldsw + _i * 8192), 16, 0, 0); } while (0)
; #define PG8_LDA(dst, b, h) do { _Pragma("unroll") for (int m = 0; m < 4; ++m) _Pragma("unroll") for (int k = 0; k < 2; ++k) dst[m][k] = *(const PG8_LAS bf16x8*)(lds + PG8_SA(b, h) + aoff + m * 2048 + k * 1024); } while (0)
; #define PG8_LDB(dst, b, h) do { _Pragma("unroll") for (int n = 0; n < 2; ++n) _Pragma("unroll") for (int k = 0; k < 2; ++k) dst[n][k] = *(const PG8_LAS bf16x8*)(lds + PG8_SB(b, h) + boff + n * 2048 + k * 1024); } while (0)
; #define PG8_MMA(ai, bj, At, Bt) do { __builtin_amdgcn_s_setprio(1); _Pragma("unroll") for (int m = 0; m < 4; ++m) _Pragma("unroll") for (int n = 0; n < 2; ++n) _Pragma("unroll") for (int k = 0; k < 2; ++k) \
;         acc[ai][bj][m][n] = __builtin_amdgcn_mfma_f32_16x16x32_bf16(Bt[n][k], At[m][k], acc[ai][bj][m][n], 0, 0, 0); __builtin_amdgcn_s_setprio(0); } while (0)
; #define PG8_WAIT_V(n) asm volatile("s_waitcnt vmcnt(" #n ")" ::: "memory")
; #define PG8_WAIT_L(n) asm volatile("s_waitcnt lgkmcnt(" #n ")" ::: "memory")
; #define PG8_BAR __builtin_amdgcn_s_barrier()
; #define PG8_SCHED __builtin_amdgcn_sched_barrier(0)
; template <class Epi, class Sched>
; __device__ __forceinline__ void gemm_phase(PG8_LAS unsigned char* lds, const Gemm g, const Sched& S, const Epi& E) {
;     ...
;             PG8_STAGE(PG8_SB(0, 1), b2 + hstep, voffB);
;             PG8_WAIT_V(6); PG8_BAR; PG8_MMA(1, 1, At, B1); PG8_BAR;
;             PG8_LDB(B0, 1, 0); PG8_SCHED; PG8_LDA(At, 1, 0); PG8_STAGE(PG8_SA(0, 1), a2 + hstep, voffA);
;             PG8_WAIT_L(8); PG8_BAR; PG8_WAIT_L(0); PG8_MMA(0, 0, At, B0); PG8_BAR; PG8_SCHED;
;             PG8_LDB(B1, 1, 1); PG8_STAGE(PG8_SB(1, 0), b3, voffB);
;             PG8_BAR; PG8_WAIT_L(0); PG8_MMA(0, 1, At, B1); PG8_BAR;
;             PG8_LDA(At, 1, 1); PG8_STAGE(PG8_SA(1, 0), a3, voffA);
;             PG8_BAR; PG8_WAIT_L(0); PG8_MMA(1, 0, At, B0); PG8_BAR; PG8_SCHED;
	s_add_u32 s46, s14, 0x40000
	s_addc_u32 s47, s15, 0
	s_add_i32 m0, s20, 0x14000
	s_nop 0
	global_load_lds_dwordx4 v176, s[46:47]
	s_add_i32 m0, s20, 0x16000
	s_nop 0
	global_load_lds_dwordx4 v128, s[46:47]
	s_waitcnt vmcnt(6)
	s_barrier
	v_mfma_f32_16x16x32_bf16 v[56:59], v[194:197], v[158:161], v[56:59]
	v_mfma_f32_16x16x32_bf16 v[48:51], v[202:205], v[158:161], v[48:51]
	v_mfma_f32_16x16x32_bf16 v[40:43], v[194:197], v[166:169], v[40:43]
	v_mfma_f32_16x16x32_bf16 v[32:35], v[202:205], v[166:169], v[32:35]
	v_mfma_f32_16x16x32_bf16 v[24:27], v[194:197], v[178:181], v[24:27]
	v_mfma_f32_16x16x32_bf16 v[16:19], v[202:205], v[178:181], v[16:19]
	v_mfma_f32_16x16x32_bf16 v[8:11], v[194:197], v[186:189], v[8:11]
	v_mfma_f32_16x16x32_bf16 v[0:3], v[202:205], v[186:189], v[0:3]
	v_mfma_f32_16x16x32_bf16 v[56:59], v[198:201], v[162:165], v[56:59]
	v_mfma_f32_16x16x32_bf16 v[48:51], v[206:209], v[162:165], v[48:51]
	v_mfma_f32_16x16x32_bf16 v[40:43], v[198:201], v[170:173], v[40:43]
	v_mfma_f32_16x16x32_bf16 v[32:35], v[206:209], v[170:173], v[32:35]
	v_mfma_f32_16x16x32_bf16 v[24:27], v[198:201], v[182:185], v[24:27]
	v_mfma_f32_16x16x32_bf16 v[16:19], v[206:209], v[182:185], v[16:19]
	v_mfma_f32_16x16x32_bf16 v[8:11], v[198:201], v[190:193], v[8:11]
	v_mfma_f32_16x16x32_bf16 v[0:3], v[206:209], v[190:193], v[0:3]
	v_add_u32_e32 v154, 0x18000, v143
	s_barrier
	ds_read_b128 v[138:141], v154
	ds_read_b128 v[146:149], v154 offset:1024
	ds_read_b128 v[150:153], v154 offset:2048
	ds_read_b128 v[154:157], v154 offset:3072
	s_add_u32 s16, s16, 0x40000
	s_addc_u32 s17, s17, 0
	s_mov_b32 m0, s23
	ds_read_b128 v[158:161], v145 offset:32768
	ds_read_b128 v[162:165], v145 offset:33792
	ds_read_b128 v[166:169], v145 offset:34816
	ds_read_b128 v[170:173], v145 offset:35840
	ds_read_b128 v[178:181], v145 offset:36864
	ds_read_b128 v[182:185], v145 offset:37888
	ds_read_b128 v[186:189], v145 offset:38912
	global_load_lds_dwordx4 v132, s[16:17]
	s_mov_b32 m0, s26
	ds_read_b128 v[190:193], v145 offset:39936
	global_load_lds_dwordx4 v130, s[16:17]
	s_waitcnt lgkmcnt(8)
	s_barrier
	s_waitcnt lgkmcnt(7)
	v_mfma_f32_16x16x32_bf16 v[124:127], v[138:141], v[158:161], v[124:127]
	v_mfma_f32_16x16x32_bf16 v[116:119], v[150:153], v[158:161], v[116:119]
	s_waitcnt lgkmcnt(5)
	v_mfma_f32_16x16x32_bf16 v[108:111], v[138:141], v[166:169], v[108:111]
	v_mfma_f32_16x16x32_bf16 v[100:103], v[150:153], v[166:169], v[100:103]
	s_waitcnt lgkmcnt(3)
	v_mfma_f32_16x16x32_bf16 v[92:95], v[138:141], v[178:181], v[92:95]
	v_mfma_f32_16x16x32_bf16 v[84:87], v[150:153], v[178:181], v[84:87]
	s_waitcnt lgkmcnt(1)
	v_mfma_f32_16x16x32_bf16 v[76:79], v[138:141], v[186:189], v[76:79]
	v_mfma_f32_16x16x32_bf16 v[68:71], v[150:153], v[186:189], v[68:71]
	v_mfma_f32_16x16x32_bf16 v[124:127], v[146:149], v[162:165], v[124:127]
	v_mfma_f32_16x16x32_bf16 v[116:119], v[154:157], v[162:165], v[116:119]
	v_mfma_f32_16x16x32_bf16 v[108:111], v[146:149], v[170:173], v[108:111]
	v_mfma_f32_16x16x32_bf16 v[100:103], v[154:157], v[170:173], v[100:103]
	v_mfma_f32_16x16x32_bf16 v[92:95], v[146:149], v[182:185], v[92:95]
	v_mfma_f32_16x16x32_bf16 v[84:87], v[154:157], v[182:185], v[84:87]
	s_waitcnt lgkmcnt(0)
	v_mfma_f32_16x16x32_bf16 v[76:79], v[146:149], v[190:193], v[76:79]
	v_mfma_f32_16x16x32_bf16 v[68:71], v[154:157], v[190:193], v[68:71]
	s_barrier
	v_add_u32_e32 v206, 0x1c000, v143
	s_add_i32 m0, s20, 0x18000
	ds_read_b128 v[194:197], v206
	ds_read_b128 v[198:201], v206 offset:1024
	ds_read_b128 v[202:205], v206 offset:2048
	global_load_lds_dwordx4 v176, s[98:99]
	s_add_i32 m0, s20, 0x1a000
	ds_read_b128 v[206:209], v206 offset:3072
	global_load_lds_dwordx4 v128, s[98:99]
	s_barrier
	s_waitcnt lgkmcnt(3)
	v_mfma_f32_16x16x32_bf16 v[120:123], v[194:197], v[158:161], v[120:123]
	s_waitcnt lgkmcnt(1)
	v_mfma_f32_16x16x32_bf16 v[112:115], v[202:205], v[158:161], v[112:115]
	v_mfma_f32_16x16x32_bf16 v[104:107], v[194:197], v[166:169], v[104:107]
	v_mfma_f32_16x16x32_bf16 v[96:99], v[202:205], v[166:169], v[96:99]
	v_mfma_f32_16x16x32_bf16 v[88:91], v[194:197], v[178:181], v[88:91]
	v_mfma_f32_16x16x32_bf16 v[80:83], v[202:205], v[178:181], v[80:83]
	v_mfma_f32_16x16x32_bf16 v[72:75], v[194:197], v[186:189], v[72:75]
	v_mfma_f32_16x16x32_bf16 v[64:67], v[202:205], v[186:189], v[64:67]
	v_mfma_f32_16x16x32_bf16 v[120:123], v[198:201], v[162:165], v[120:123]
	s_waitcnt lgkmcnt(0)
	v_mfma_f32_16x16x32_bf16 v[112:115], v[206:209], v[162:165], v[112:115]
	v_mfma_f32_16x16x32_bf16 v[104:107], v[198:201], v[170:173], v[104:107]
	v_mfma_f32_16x16x32_bf16 v[96:99], v[206:209], v[170:173], v[96:99]
	v_mfma_f32_16x16x32_bf16 v[88:91], v[198:201], v[182:185], v[88:91]
	v_mfma_f32_16x16x32_bf16 v[80:83], v[206:209], v[182:185], v[80:83]
	v_mfma_f32_16x16x32_bf16 v[72:75], v[198:201], v[190:193], v[72:75]
	v_mfma_f32_16x16x32_bf16 v[64:67], v[206:209], v[190:193], v[64:67]
	s_mov_b32 m0, s28
	s_barrier
	ds_read_b128 v[158:161], v145 offset:49152
	ds_read_b128 v[162:165], v145 offset:50176
	ds_read_b128 v[166:169], v145 offset:51200
	ds_read_b128 v[170:173], v145 offset:52224
	ds_read_b128 v[178:181], v145 offset:53248
	ds_read_b128 v[182:185], v145 offset:54272
	ds_read_b128 v[186:189], v145 offset:55296
	global_load_lds_dwordx4 v132, s[100:101]
	s_mov_b32 m0, s29
	ds_read_b128 v[190:193], v145 offset:56320
	global_load_lds_dwordx4 v130, s[100:101]
	s_barrier
; __device__ __forceinline__ unsigned cvtpk(float lo, float hi) { const f32x2 v = (f32x2){lo, hi}; const bf16v2 b = __builtin_convertvector(v, bf16v2); return __builtin_bit_cast(unsigned, b); }
; __device__ __forceinline__ float siluf_(float x) { return x * sigmoidf_(x); }
; #define PG8_STAGE(bufoff, gbase, voff) do { _Pragma("unroll") for (int _i = 0; _i < 2; ++_i) \
;         __builtin_amdgcn_global_load_lds((const unsigned*)((const char*)(gbase) + (voff)[_i]), (PG8_LAS unsigned*)(lds + (bufoff) + ldsw + _i * 8192), 16, 0, 0); } while (0)
; #define PG8_MMA(ai, bj, At, Bt) do { __builtin_amdgcn_s_setprio(1); _Pragma("unroll") for (int m = 0; m < 4; ++m) _Pragma("unroll") for (int n = 0; n < 2; ++n) _Pragma("unroll") for (int k = 0; k < 2; ++k) \
;         acc[ai][bj][m][n] = __builtin_amdgcn_mfma_f32_16x16x32_bf16(Bt[n][k], At[m][k], acc[ai][bj][m][n], 0, 0, 0); __builtin_amdgcn_s_setprio(0); } while (0)
; #define PG8_WAIT_V(n) asm volatile("s_waitcnt vmcnt(" #n ")" ::: "memory")
; #define PG8_WAIT_L(n) asm volatile("s_waitcnt lgkmcnt(" #n ")" ::: "memory")
; #define PG8_BAR __builtin_amdgcn_s_barrier()
; template <class Epi, class Sched>
; __device__ __forceinline__ void gemm_phase(PG8_LAS unsigned char* lds, const Gemm g, const Sched& S, const Epi& E) {
;     ...
;             PG8_BAR; PG8_WAIT_L(0); PG8_MMA(1, 0, At, B0); PG8_BAR; PG8_SCHED;
;             PG8_STAGE(PG8_SB(1, 1), b3 + hstep, voffB);
;             PG8_WAIT_V(6); PG8_BAR; PG8_MMA(1, 1, At, B1); PG8_BAR;
;         }
;     __device__ __forceinline__ void operator()(const f32x4 (&acc)[2][2][4][2], const pg8::Unit& u, int wr, int wc, int fr, int fq) const {
;         const int row0 = u.pm * 256 + wr * 64 + fr, col0 = u.pn * 128 + wc * 32 + 8 * fq;
; #pragma unroll
;         for (int ai = 0; ai < 2; ++ai)
; #pragma unroll
;             for (int m = 0; m < 4; ++m) { bf16_t* rowp = O + (size_t)(row0 + ai * 128 + m * 16) * ldc + col0;
;                 const f32x4 g0 = acc[ai][0][m][0], g1 = acc[ai][0][m][1], u0 = acc[ai][1][m][0], u1 = acc[ai][1][m][1];
;                 u32x4 w; w.x = cvtpk(siluf_(g0[0]) * u0[0], siluf_(g0[1]) * u0[1]); w.y = cvtpk(siluf_(g0[2]) * u0[2], siluf_(g0[3]) * u0[3]);
;                 w.z = cvtpk(siluf_(g1[0]) * u1[0], siluf_(g1[1]) * u1[1]); w.w = cvtpk(siluf_(g1[2]) * u1[2], siluf_(g1[3]) * u1[3]);
;                 *(u32x4*)rowp = w; }
	s_waitcnt lgkmcnt(7)
	v_mfma_f32_16x16x32_bf16 v[60:63], v[138:141], v[158:161], v[60:63]
	v_mfma_f32_16x16x32_bf16 v[52:55], v[150:153], v[158:161], v[52:55]
	s_waitcnt lgkmcnt(5)
	v_mfma_f32_16x16x32_bf16 v[44:47], v[138:141], v[166:169], v[44:47]
	v_mfma_f32_16x16x32_bf16 v[36:39], v[150:153], v[166:169], v[36:39]
	s_waitcnt lgkmcnt(3)
	v_mfma_f32_16x16x32_bf16 v[28:31], v[138:141], v[178:181], v[28:31]
	v_mfma_f32_16x16x32_bf16 v[20:23], v[150:153], v[178:181], v[20:23]
	s_waitcnt lgkmcnt(1)
	v_mfma_f32_16x16x32_bf16 v[12:15], v[138:141], v[186:189], v[12:15]
	v_mfma_f32_16x16x32_bf16 v[4:7], v[150:153], v[186:189], v[4:7]
	v_mfma_f32_16x16x32_bf16 v[60:63], v[146:149], v[162:165], v[60:63]
	v_mfma_f32_16x16x32_bf16 v[52:55], v[154:157], v[162:165], v[52:55]
	v_mfma_f32_16x16x32_bf16 v[44:47], v[146:149], v[170:173], v[44:47]
	v_mfma_f32_16x16x32_bf16 v[36:39], v[154:157], v[170:173], v[36:39]
	v_mfma_f32_16x16x32_bf16 v[28:31], v[146:149], v[182:185], v[28:31]
	v_mfma_f32_16x16x32_bf16 v[20:23], v[154:157], v[182:185], v[20:23]
	s_waitcnt lgkmcnt(0)
	v_mfma_f32_16x16x32_bf16 v[12:15], v[146:149], v[190:193], v[12:15]
	v_mfma_f32_16x16x32_bf16 v[4:7], v[154:157], v[190:193], v[4:7]
	s_barrier
	s_add_u32 s14, s14, 0x40080
	s_addc_u32 s15, s15, 0
	s_add_i32 m0, s20, 0x1c000
	s_nop 0
	global_load_lds_dwordx4 v176, s[14:15]
	s_add_i32 m0, s20, 0x1e000
	s_nop 0
	global_load_lds_dwordx4 v128, s[14:15]
	s_waitcnt vmcnt(6)
	s_barrier
	v_mfma_f32_16x16x32_bf16 v[56:59], v[194:197], v[158:161], v[56:59]
	v_mfma_f32_16x16x32_bf16 v[48:51], v[202:205], v[158:161], v[48:51]
	v_mfma_f32_16x16x32_bf16 v[40:43], v[194:197], v[166:169], v[40:43]
	v_mfma_f32_16x16x32_bf16 v[32:35], v[202:205], v[166:169], v[32:35]
	v_mfma_f32_16x16x32_bf16 v[24:27], v[194:197], v[178:181], v[24:27]
	v_mfma_f32_16x16x32_bf16 v[16:19], v[202:205], v[178:181], v[16:19]
	v_mfma_f32_16x16x32_bf16 v[8:11], v[194:197], v[186:189], v[8:11]
	v_mfma_f32_16x16x32_bf16 v[0:3], v[202:205], v[186:189], v[0:3]
	v_mfma_f32_16x16x32_bf16 v[56:59], v[198:201], v[162:165], v[56:59]
	v_mfma_f32_16x16x32_bf16 v[48:51], v[206:209], v[162:165], v[48:51]
	v_mfma_f32_16x16x32_bf16 v[40:43], v[198:201], v[170:173], v[40:43]
	v_mfma_f32_16x16x32_bf16 v[32:35], v[206:209], v[170:173], v[32:35]
	v_mfma_f32_16x16x32_bf16 v[24:27], v[198:201], v[182:185], v[24:27]
	v_mfma_f32_16x16x32_bf16 v[16:19], v[206:209], v[182:185], v[16:19]
	v_mfma_f32_16x16x32_bf16 v[8:11], v[198:201], v[190:193], v[8:11]
	v_mfma_f32_16x16x32_bf16 v[0:3], v[206:209], v[190:193], v[0:3]
	s_add_i32 s45, s45, 2
	s_add_u32 s12, s12, 0x100
	s_addc_u32 s13, s13, 0
	s_add_u32 s43, s43, 0x100
	s_addc_u32 s44, s44, 0
	s_cmp_gt_u32 s45, 13
	s_barrier
	s_cbranch_scc0 .LBB0_114
	v_mul_f32_e32 v147, 0xbfb8aa3b, v124
	v_exp_f32_e32 v147, v147
	v_readlane_b32 s12, v253, 16
	v_lshl_add_u32 v146, s10, 8, v142
	v_lshl_or_b32 v140, s34, 7, v144
	v_add_f32_e32 v147, 1.0, v147
	v_rcp_f32_e32 v150, v147
	v_mul_f32_e32 v147, 0xbfb8aa3b, v125
	v_exp_f32_e32 v147, v147
	v_readlane_b32 s13, v253, 17
	v_ashrrev_i32_e32 v141, 31, v140
	v_lshlrev_b64 v[140:141], 1, v[140:141]
	v_add_f32_e32 v147, 1.0, v147
	v_rcp_f32_e32 v151, v147
	v_mov_b64_e32 v[138:139], s[12:13]
	v_mad_i64_i32 v[148:149], s[12:13], v146, s81, v[138:139]
	v_pk_mul_f32 v[124:125], v[124:125], v[150:151]
	v_lshl_add_u64 v[148:149], v[148:149], 0, v[140:141]
	v_pk_mul_f32 v[120:121], v[124:125], v[120:121]
	s_and_b64 vcc, exec, s[38:39]
	v_cvt_pk_bf16_f32 v120, v120, v121
	v_mul_f32_e32 v121, 0xbfb8aa3b, v126
	v_exp_f32_e32 v121, v121
	s_mov_b32 s34, s0
	s_mov_b32 s10, s4
	s_mov_b64 s[14:15], s[8:9]
	v_add_f32_e32 v121, 1.0, v121
	v_rcp_f32_e32 v124, v121
	v_mul_f32_e32 v121, 0xbfb8aa3b, v127
	v_exp_f32_e32 v121, v121
	s_nop 0
	v_add_f32_e32 v121, 1.0, v121
	v_rcp_f32_e32 v125, v121
	s_nop 0
	v_pk_mul_f32 v[124:125], v[126:127], v[124:125]
	s_nop 0
	v_pk_mul_f32 v[122:123], v[124:125], v[122:123]
	s_nop 0
	v_cvt_pk_bf16_f32 v121, v122, v123
	v_mul_f32_e32 v122, 0xbfb8aa3b, v116
	v_mul_f32_e32 v123, 0xbfb8aa3b, v117
	v_exp_f32_e32 v122, v122
	v_exp_f32_e32 v123, v123
	v_add_f32_e32 v122, 1.0, v122
	v_add_f32_e32 v123, 1.0, v123
	v_rcp_f32_e32 v122, v122
	v_rcp_f32_e32 v123, v123
	s_nop 0
	v_pk_mul_f32 v[116:117], v[116:117], v[122:123]
	s_nop 0
	v_pk_mul_f32 v[112:113], v[116:117], v[112:113]
	s_nop 0
	v_cvt_pk_bf16_f32 v122, v112, v113
	v_mul_f32_e32 v112, 0xbfb8aa3b, v118
	v_mul_f32_e32 v113, 0xbfb8aa3b, v119
	v_exp_f32_e32 v112, v112
	v_exp_f32_e32 v113, v113
	v_add_f32_e32 v112, 1.0, v112
	v_add_f32_e32 v113, 1.0, v113
	v_rcp_f32_e32 v112, v112
	v_rcp_f32_e32 v113, v113
	s_nop 0
	v_pk_mul_f32 v[112:113], v[118:119], v[112:113]
	s_nop 0
	v_pk_mul_f32 v[112:113], v[112:113], v[114:115]
	v_mul_f32_e32 v114, 0xbfb8aa3b, v108
	v_mul_f32_e32 v115, 0xbfb8aa3b, v109
	v_exp_f32_e32 v114, v114
	v_exp_f32_e32 v115, v115
	v_cvt_pk_bf16_f32 v123, v112, v113
	v_or_b32_e32 v112, 16, v146
	v_add_f32_e32 v114, 1.0, v114
	v_add_f32_e32 v115, 1.0, v115
	v_rcp_f32_e32 v114, v114
	v_rcp_f32_e32 v115, v115
	v_mad_i64_i32 v[112:113], s[12:13], v112, s81, v[138:139]
	v_lshl_add_u64 v[112:113], v[112:113], 0, v[140:141]
	v_pk_mul_f32 v[108:109], v[108:109], v[114:115]
	global_store_dwordx4 v[148:149], v[120:123], off
	v_pk_mul_f32 v[104:105], v[108:109], v[104:105]
	s_nop 0
	v_cvt_pk_bf16_f32 v104, v104, v105
	v_mul_f32_e32 v105, 0xbfb8aa3b, v110
	v_exp_f32_e32 v105, v105
	s_nop 0
	v_add_f32_e32 v105, 1.0, v105
	v_rcp_f32_e32 v108, v105
	v_mul_f32_e32 v105, 0xbfb8aa3b, v111
	v_exp_f32_e32 v105, v105
	s_nop 0
	v_add_f32_e32 v105, 1.0, v105
	v_rcp_f32_e32 v109, v105
	s_nop 0
	v_pk_mul_f32 v[108:109], v[110:111], v[108:109]
; __device__ __forceinline__ unsigned cvtpk(float lo, float hi) { const f32x2 v = (f32x2){lo, hi}; const bf16v2 b = __builtin_convertvector(v, bf16v2); return __builtin_bit_cast(unsigned, b); }
; __device__ __forceinline__ float siluf_(float x) { return x * sigmoidf_(x); }
;     __device__ __forceinline__ void operator()(const f32x4 (&acc)[2][2][4][2], const pg8::Unit& u, int wr, int wc, int fr, int fq) const {
;         const int row0 = u.pm * 256 + wr * 64 + fr, col0 = u.pn * 128 + wc * 32 + 8 * fq;
; #pragma unroll
;         for (int ai = 0; ai < 2; ++ai)
; #pragma unroll
;             for (int m = 0; m < 4; ++m) { bf16_t* rowp = O + (size_t)(row0 + ai * 128 + m * 16) * ldc + col0;
;                 const f32x4 g0 = acc[ai][0][m][0], g1 = acc[ai][0][m][1], u0 = acc[ai][1][m][0], u1 = acc[ai][1][m][1];
;                 u32x4 w; w.x = cvtpk(siluf_(g0[0]) * u0[0], siluf_(g0[1]) * u0[1]); w.y = cvtpk(siluf_(g0[2]) * u0[2], siluf_(g0[3]) * u0[3]);
;                 w.z = cvtpk(siluf_(g1[0]) * u1[0], siluf_(g1[1]) * u1[1]); w.w = cvtpk(siluf_(g1[2]) * u1[2], siluf_(g1[3]) * u1[3]);
;                 *(u32x4*)rowp = w; }
	s_nop 0
	v_pk_mul_f32 v[106:107], v[108:109], v[106:107]
	s_nop 0
	v_cvt_pk_bf16_f32 v105, v106, v107
	v_mul_f32_e32 v106, 0xbfb8aa3b, v100
	v_mul_f32_e32 v107, 0xbfb8aa3b, v101
	v_exp_f32_e32 v106, v106
	v_exp_f32_e32 v107, v107
	v_add_f32_e32 v106, 1.0, v106
	v_add_f32_e32 v107, 1.0, v107
	v_rcp_f32_e32 v106, v106
	v_rcp_f32_e32 v107, v107
	s_nop 0
	v_pk_mul_f32 v[100:101], v[100:101], v[106:107]
	s_nop 0
	v_pk_mul_f32 v[96:97], v[100:101], v[96:97]
	s_nop 0
	v_cvt_pk_bf16_f32 v106, v96, v97
	v_mul_f32_e32 v96, 0xbfb8aa3b, v102
	v_mul_f32_e32 v97, 0xbfb8aa3b, v103
	v_exp_f32_e32 v96, v96
	v_exp_f32_e32 v97, v97
	v_add_f32_e32 v96, 1.0, v96
	v_add_f32_e32 v97, 1.0, v97
	v_rcp_f32_e32 v96, v96
	v_rcp_f32_e32 v97, v97
	s_nop 0
	v_pk_mul_f32 v[96:97], v[102:103], v[96:97]
	s_nop 0
	v_pk_mul_f32 v[96:97], v[96:97], v[98:99]
	v_mul_f32_e32 v98, 0xbfb8aa3b, v92
	v_mul_f32_e32 v99, 0xbfb8aa3b, v93
	v_exp_f32_e32 v98, v98
	v_exp_f32_e32 v99, v99
	v_cvt_pk_bf16_f32 v107, v96, v97
	v_or_b32_e32 v96, 32, v146
	v_add_f32_e32 v98, 1.0, v98
	v_add_f32_e32 v99, 1.0, v99
	v_rcp_f32_e32 v98, v98
	v_rcp_f32_e32 v99, v99
	v_mad_i64_i32 v[96:97], s[12:13], v96, s81, v[138:139]
	v_lshl_add_u64 v[96:97], v[96:97], 0, v[140:141]
	v_pk_mul_f32 v[92:93], v[92:93], v[98:99]
	global_store_dwordx4 v[112:113], v[104:107], off
	v_pk_mul_f32 v[88:89], v[92:93], v[88:89]
	s_nop 0
	v_cvt_pk_bf16_f32 v88, v88, v89
	v_mul_f32_e32 v89, 0xbfb8aa3b, v94
	v_exp_f32_e32 v89, v89
	s_nop 0
	v_add_f32_e32 v89, 1.0, v89
	v_rcp_f32_e32 v92, v89
	v_mul_f32_e32 v89, 0xbfb8aa3b, v95
	v_exp_f32_e32 v89, v89
	s_nop 0
	v_add_f32_e32 v89, 1.0, v89
	v_rcp_f32_e32 v93, v89
	s_nop 0
	v_pk_mul_f32 v[92:93], v[94:95], v[92:93]
	s_nop 0
	v_pk_mul_f32 v[90:91], v[92:93], v[90:91]
	s_nop 0
	v_cvt_pk_bf16_f32 v89, v90, v91
	v_mul_f32_e32 v90, 0xbfb8aa3b, v84
	v_mul_f32_e32 v91, 0xbfb8aa3b, v85
	v_exp_f32_e32 v90, v90
	v_exp_f32_e32 v91, v91
	v_add_f32_e32 v90, 1.0, v90
	v_add_f32_e32 v91, 1.0, v91
	v_rcp_f32_e32 v90, v90
	v_rcp_f32_e32 v91, v91
	s_nop 0
	v_pk_mul_f32 v[84:85], v[84:85], v[90:91]
	s_nop 0
	v_pk_mul_f32 v[80:81], v[84:85], v[80:81]
	s_nop 0
	v_cvt_pk_bf16_f32 v90, v80, v81
	v_mul_f32_e32 v80, 0xbfb8aa3b, v86
	v_mul_f32_e32 v81, 0xbfb8aa3b, v87
	v_exp_f32_e32 v80, v80
	v_exp_f32_e32 v81, v81
	v_add_f32_e32 v80, 1.0, v80
	v_add_f32_e32 v81, 1.0, v81
	v_rcp_f32_e32 v80, v80
	v_rcp_f32_e32 v81, v81
	s_nop 0
	v_pk_mul_f32 v[80:81], v[86:87], v[80:81]
	s_nop 0
	v_pk_mul_f32 v[80:81], v[80:81], v[82:83]
	v_mul_f32_e32 v82, 0xbfb8aa3b, v76
	v_mul_f32_e32 v83, 0xbfb8aa3b, v77
	v_exp_f32_e32 v82, v82
	v_exp_f32_e32 v83, v83
	v_cvt_pk_bf16_f32 v91, v80, v81
	v_or_b32_e32 v80, 48, v146
	v_add_f32_e32 v82, 1.0, v82
	v_add_f32_e32 v83, 1.0, v83
	v_rcp_f32_e32 v82, v82
	v_rcp_f32_e32 v83, v83
	v_mad_i64_i32 v[80:81], s[12:13], v80, s81, v[138:139]
	v_lshl_add_u64 v[80:81], v[80:81], 0, v[140:141]
	v_pk_mul_f32 v[76:77], v[76:77], v[82:83]
	global_store_dwordx4 v[96:97], v[88:91], off
	v_pk_mul_f32 v[72:73], v[76:77], v[72:73]
	s_nop 0
	v_cvt_pk_bf16_f32 v72, v72, v73
	v_mul_f32_e32 v73, 0xbfb8aa3b, v78
	v_exp_f32_e32 v73, v73
	s_nop 0
	v_add_f32_e32 v73, 1.0, v73
	v_rcp_f32_e32 v76, v73
	v_mul_f32_e32 v73, 0xbfb8aa3b, v79
	v_exp_f32_e32 v73, v73
	s_nop 0
	v_add_f32_e32 v73, 1.0, v73
	v_rcp_f32_e32 v77, v73
	s_nop 0
	v_pk_mul_f32 v[76:77], v[78:79], v[76:77]
	s_nop 0
	v_pk_mul_f32 v[74:75], v[76:77], v[74:75]
	s_nop 0
	v_cvt_pk_bf16_f32 v73, v74, v75
	v_mul_f32_e32 v74, 0xbfb8aa3b, v68
	v_mul_f32_e32 v75, 0xbfb8aa3b, v69
	v_exp_f32_e32 v74, v74
	v_exp_f32_e32 v75, v75
	v_add_f32_e32 v74, 1.0, v74
	v_add_f32_e32 v75, 1.0, v75
	v_rcp_f32_e32 v74, v74
	v_rcp_f32_e32 v75, v75
	s_nop 0
	v_pk_mul_f32 v[68:69], v[68:69], v[74:75]
	s_nop 0
	v_pk_mul_f32 v[64:65], v[68:69], v[64:65]
	s_nop 0
	v_cvt_pk_bf16_f32 v74, v64, v65
	v_mul_f32_e32 v64, 0xbfb8aa3b, v70
	v_mul_f32_e32 v65, 0xbfb8aa3b, v71
	v_exp_f32_e32 v64, v64
	v_exp_f32_e32 v65, v65
	v_add_f32_e32 v64, 1.0, v64
	v_add_f32_e32 v65, 1.0, v65
	v_rcp_f32_e32 v64, v64
	v_rcp_f32_e32 v65, v65
	s_nop 0
	v_pk_mul_f32 v[64:65], v[70:71], v[64:65]
	s_nop 0
	v_pk_mul_f32 v[64:65], v[64:65], v[66:67]
	v_mul_f32_e32 v66, 0xbfb8aa3b, v60
	v_mul_f32_e32 v67, 0xbfb8aa3b, v61
	v_exp_f32_e32 v66, v66
	v_exp_f32_e32 v67, v67
	v_cvt_pk_bf16_f32 v75, v64, v65
	v_add_u32_e32 v64, 0x80, v146
	v_add_f32_e32 v66, 1.0, v66
	v_add_f32_e32 v67, 1.0, v67
	v_rcp_f32_e32 v66, v66
	v_rcp_f32_e32 v67, v67
	v_mad_i64_i32 v[64:65], s[12:13], v64, s81, v[138:139]
	v_lshl_add_u64 v[64:65], v[64:65], 0, v[140:141]
	v_pk_mul_f32 v[60:61], v[60:61], v[66:67]
	global_store_dwordx4 v[80:81], v[72:75], off
	v_pk_mul_f32 v[56:57], v[60:61], v[56:57]
	s_nop 0
	v_cvt_pk_bf16_f32 v56, v56, v57
	v_mul_f32_e32 v57, 0xbfb8aa3b, v62
	v_exp_f32_e32 v57, v57
	s_nop 0
	v_add_f32_e32 v57, 1.0, v57
	v_rcp_f32_e32 v60, v57
	v_mul_f32_e32 v57, 0xbfb8aa3b, v63
	v_exp_f32_e32 v57, v57
	s_nop 0
	v_add_f32_e32 v57, 1.0, v57
	v_rcp_f32_e32 v61, v57
	s_nop 0
	v_pk_mul_f32 v[60:61], v[62:63], v[60:61]
	s_nop 0
	v_pk_mul_f32 v[58:59], v[60:61], v[58:59]
	s_nop 0
	v_cvt_pk_bf16_f32 v57, v58, v59
	v_mul_f32_e32 v58, 0xbfb8aa3b, v52
	v_mul_f32_e32 v59, 0xbfb8aa3b, v53
	v_exp_f32_e32 v58, v58
	v_exp_f32_e32 v59, v59
	v_add_f32_e32 v58, 1.0, v58
	v_add_f32_e32 v59, 1.0, v59
	v_rcp_f32_e32 v58, v58
	v_rcp_f32_e32 v59, v59
	s_nop 0
	v_pk_mul_f32 v[52:53], v[52:53], v[58:59]
	s_nop 0
	v_pk_mul_f32 v[48:49], v[52:53], v[48:49]
	s_nop 0
	v_cvt_pk_bf16_f32 v58, v48, v49
	v_mul_f32_e32 v48, 0xbfb8aa3b, v54
; __device__ __forceinline__ unsigned cvtpk(float lo, float hi) { const f32x2 v = (f32x2){lo, hi}; const bf16v2 b = __builtin_convertvector(v, bf16v2); return __builtin_bit_cast(unsigned, b); }
; __device__ __forceinline__ float siluf_(float x) { return x * sigmoidf_(x); }
;     __device__ __forceinline__ void operator()(const f32x4 (&acc)[2][2][4][2], const pg8::Unit& u, int wr, int wc, int fr, int fq) const {
;         const int row0 = u.pm * 256 + wr * 64 + fr, col0 = u.pn * 128 + wc * 32 + 8 * fq;
; #pragma unroll
;         for (int ai = 0; ai < 2; ++ai)
; #pragma unroll
;             for (int m = 0; m < 4; ++m) { bf16_t* rowp = O + (size_t)(row0 + ai * 128 + m * 16) * ldc + col0;
;                 const f32x4 g0 = acc[ai][0][m][0], g1 = acc[ai][0][m][1], u0 = acc[ai][1][m][0], u1 = acc[ai][1][m][1];
;                 u32x4 w; w.x = cvtpk(siluf_(g0[0]) * u0[0], siluf_(g0[1]) * u0[1]); w.y = cvtpk(siluf_(g0[2]) * u0[2], siluf_(g0[3]) * u0[3]);
;                 w.z = cvtpk(siluf_(g1[0]) * u1[0], siluf_(g1[1]) * u1[1]); w.w = cvtpk(siluf_(g1[2]) * u1[2], siluf_(g1[3]) * u1[3]);
;                 *(u32x4*)rowp = w; }
	v_mul_f32_e32 v49, 0xbfb8aa3b, v55
	v_exp_f32_e32 v48, v48
	v_exp_f32_e32 v49, v49
	v_add_f32_e32 v48, 1.0, v48
	v_add_f32_e32 v49, 1.0, v49
	v_rcp_f32_e32 v48, v48
	v_rcp_f32_e32 v49, v49
	s_nop 0
	v_pk_mul_f32 v[48:49], v[54:55], v[48:49]
	s_nop 0
	v_pk_mul_f32 v[48:49], v[48:49], v[50:51]
	v_mul_f32_e32 v50, 0xbfb8aa3b, v44
	v_mul_f32_e32 v51, 0xbfb8aa3b, v45
	v_exp_f32_e32 v50, v50
	v_exp_f32_e32 v51, v51
	v_cvt_pk_bf16_f32 v59, v48, v49
	v_add_u32_e32 v48, 0x90, v146
	v_add_f32_e32 v50, 1.0, v50
	v_add_f32_e32 v51, 1.0, v51
	v_rcp_f32_e32 v50, v50
	v_rcp_f32_e32 v51, v51
	v_mad_i64_i32 v[48:49], s[12:13], v48, s81, v[138:139]
	v_lshl_add_u64 v[48:49], v[48:49], 0, v[140:141]
	v_pk_mul_f32 v[44:45], v[44:45], v[50:51]
	global_store_dwordx4 v[64:65], v[56:59], off
	v_pk_mul_f32 v[40:41], v[44:45], v[40:41]
	s_nop 0
	v_cvt_pk_bf16_f32 v40, v40, v41
	v_mul_f32_e32 v41, 0xbfb8aa3b, v46
	v_exp_f32_e32 v41, v41
	s_nop 0
	v_add_f32_e32 v41, 1.0, v41
	v_rcp_f32_e32 v44, v41
	v_mul_f32_e32 v41, 0xbfb8aa3b, v47
	v_exp_f32_e32 v41, v41
	s_nop 0
	v_add_f32_e32 v41, 1.0, v41
	v_rcp_f32_e32 v45, v41
	s_nop 0
	v_pk_mul_f32 v[44:45], v[46:47], v[44:45]
	s_nop 0
	v_pk_mul_f32 v[42:43], v[44:45], v[42:43]
	s_nop 0
	v_cvt_pk_bf16_f32 v41, v42, v43
	v_mul_f32_e32 v42, 0xbfb8aa3b, v36
	v_mul_f32_e32 v43, 0xbfb8aa3b, v37
	v_exp_f32_e32 v42, v42
	v_exp_f32_e32 v43, v43
	v_add_f32_e32 v42, 1.0, v42
	v_add_f32_e32 v43, 1.0, v43
	v_rcp_f32_e32 v42, v42
	v_rcp_f32_e32 v43, v43
	s_nop 0
	v_pk_mul_f32 v[36:37], v[36:37], v[42:43]
	s_nop 0
	v_pk_mul_f32 v[32:33], v[36:37], v[32:33]
	s_nop 0
	v_cvt_pk_bf16_f32 v42, v32, v33
	v_mul_f32_e32 v32, 0xbfb8aa3b, v38
	v_mul_f32_e32 v33, 0xbfb8aa3b, v39
	v_exp_f32_e32 v32, v32
	v_exp_f32_e32 v33, v33
	v_add_f32_e32 v32, 1.0, v32
	v_add_f32_e32 v33, 1.0, v33
	v_rcp_f32_e32 v32, v32
	v_rcp_f32_e32 v33, v33
	s_nop 0
	v_pk_mul_f32 v[32:33], v[38:39], v[32:33]
	s_nop 0
	v_pk_mul_f32 v[32:33], v[32:33], v[34:35]
	v_mul_f32_e32 v34, 0xbfb8aa3b, v28
	v_mul_f32_e32 v35, 0xbfb8aa3b, v29
	v_exp_f32_e32 v34, v34
	v_exp_f32_e32 v35, v35
	v_cvt_pk_bf16_f32 v43, v32, v33
	v_add_u32_e32 v32, 0xa0, v146
	v_add_f32_e32 v34, 1.0, v34
	v_add_f32_e32 v35, 1.0, v35
	v_rcp_f32_e32 v34, v34
	v_rcp_f32_e32 v35, v35
	v_mad_i64_i32 v[32:33], s[12:13], v32, s81, v[138:139]
	v_lshl_add_u64 v[32:33], v[32:33], 0, v[140:141]
	v_pk_mul_f32 v[28:29], v[28:29], v[34:35]
	global_store_dwordx4 v[48:49], v[40:43], off
	v_pk_mul_f32 v[24:25], v[28:29], v[24:25]
	s_nop 0
	v_cvt_pk_bf16_f32 v24, v24, v25
	v_mul_f32_e32 v25, 0xbfb8aa3b, v30
	v_exp_f32_e32 v25, v25
	s_nop 0
	v_add_f32_e32 v25, 1.0, v25
	v_rcp_f32_e32 v28, v25
	v_mul_f32_e32 v25, 0xbfb8aa3b, v31
	v_exp_f32_e32 v25, v25
	s_nop 0
	v_add_f32_e32 v25, 1.0, v25
	v_rcp_f32_e32 v29, v25
	s_nop 0
	v_pk_mul_f32 v[28:29], v[30:31], v[28:29]
	s_nop 0
	v_pk_mul_f32 v[26:27], v[28:29], v[26:27]
	s_nop 0
	v_cvt_pk_bf16_f32 v25, v26, v27
	v_mul_f32_e32 v26, 0xbfb8aa3b, v20
	v_mul_f32_e32 v27, 0xbfb8aa3b, v21
	v_exp_f32_e32 v26, v26
	v_exp_f32_e32 v27, v27
	v_add_f32_e32 v26, 1.0, v26
	v_add_f32_e32 v27, 1.0, v27
	v_rcp_f32_e32 v26, v26
	v_rcp_f32_e32 v27, v27
	s_nop 0
	v_pk_mul_f32 v[20:21], v[20:21], v[26:27]
	s_nop 0
	v_pk_mul_f32 v[16:17], v[20:21], v[16:17]
	s_nop 0
	v_cvt_pk_bf16_f32 v26, v16, v17
	v_mul_f32_e32 v16, 0xbfb8aa3b, v22
	v_mul_f32_e32 v17, 0xbfb8aa3b, v23
	v_exp_f32_e32 v16, v16
	v_exp_f32_e32 v17, v17
	v_add_f32_e32 v16, 1.0, v16
	v_add_f32_e32 v17, 1.0, v17
	v_rcp_f32_e32 v16, v16
	v_rcp_f32_e32 v17, v17
	s_nop 0
	v_pk_mul_f32 v[16:17], v[22:23], v[16:17]
	s_nop 0
	v_pk_mul_f32 v[16:17], v[16:17], v[18:19]
	v_mul_f32_e32 v18, 0xbfb8aa3b, v12
	v_mul_f32_e32 v19, 0xbfb8aa3b, v13
	v_exp_f32_e32 v18, v18
	v_exp_f32_e32 v19, v19
	v_cvt_pk_bf16_f32 v27, v16, v17
	v_add_u32_e32 v16, 0xb0, v146
	v_add_f32_e32 v18, 1.0, v18
	v_add_f32_e32 v19, 1.0, v19
	v_rcp_f32_e32 v18, v18
	v_rcp_f32_e32 v19, v19
	v_mad_i64_i32 v[16:17], s[12:13], v16, s81, v[138:139]
	v_lshl_add_u64 v[16:17], v[16:17], 0, v[140:141]
	v_pk_mul_f32 v[12:13], v[12:13], v[18:19]
	s_mov_b64 s[12:13], s[6:7]
	v_pk_mul_f32 v[8:9], v[12:13], v[8:9]
	global_store_dwordx4 v[32:33], v[24:27], off
	v_cvt_pk_bf16_f32 v8, v8, v9
	v_mul_f32_e32 v9, 0xbfb8aa3b, v14
	v_exp_f32_e32 v9, v9
	s_nop 0
	v_add_f32_e32 v9, 1.0, v9
	v_rcp_f32_e32 v12, v9
	v_mul_f32_e32 v9, 0xbfb8aa3b, v15
	v_exp_f32_e32 v9, v9
	s_nop 0
	v_add_f32_e32 v9, 1.0, v9
	v_rcp_f32_e32 v13, v9
	s_nop 0
	v_pk_mul_f32 v[12:13], v[14:15], v[12:13]
	s_nop 0
	v_pk_mul_f32 v[10:11], v[12:13], v[10:11]
	s_nop 0
	v_cvt_pk_bf16_f32 v9, v10, v11
	v_mul_f32_e32 v10, 0xbfb8aa3b, v4
	v_mul_f32_e32 v11, 0xbfb8aa3b, v5
	v_exp_f32_e32 v10, v10
	v_exp_f32_e32 v11, v11
	v_add_f32_e32 v10, 1.0, v10
	v_add_f32_e32 v11, 1.0, v11
	v_rcp_f32_e32 v10, v10
	v_rcp_f32_e32 v11, v11
	s_nop 0
	v_pk_mul_f32 v[4:5], v[4:5], v[10:11]
	s_nop 0
	v_pk_mul_f32 v[0:1], v[4:5], v[0:1]
	s_nop 0
	v_cvt_pk_bf16_f32 v10, v0, v1
	v_mul_f32_e32 v0, 0xbfb8aa3b, v6
	v_mul_f32_e32 v1, 0xbfb8aa3b, v7
	v_exp_f32_e32 v0, v0
	v_exp_f32_e32 v1, v1
	v_add_f32_e32 v0, 1.0, v0
	v_add_f32_e32 v1, 1.0, v1
	v_rcp_f32_e32 v0, v0
	v_rcp_f32_e32 v1, v1
	s_nop 0
	v_pk_mul_f32 v[0:1], v[6:7], v[0:1]
	s_nop 0
	v_pk_mul_f32 v[0:1], v[0:1], v[2:3]
	s_nop 0
	v_cvt_pk_bf16_f32 v11, v0, v1
	global_store_dwordx4 v[16:17], v[8:11], off
	s_cbranch_vccz .LBB0_111
	s_waitcnt vmcnt(0)
	v_readlane_b32 s22, v255, 14
	s_cmpk_gt_u32 s19, 0xff
	v_readlane_b32 s23, v255, 15
	s_mov_b64 s[28:29], s[54:55]
	s_cbranch_scc1 .LBB0_118
	s_barrier

; #define PG8_STAGE(bufoff, gbase, voff) do { _Pragma("unroll") for (int _i = 0; _i < 2; ++_i) \
;         __builtin_amdgcn_global_load_lds((const unsigned*)((const char*)(gbase) + (voff)[_i]), (PG8_LAS unsigned*)(lds + (bufoff) + ldsw + _i * 8192), 16, 0, 0); } while (0)
; #define PG8_LDA(dst, b, h) do { _Pragma("unroll") for (int m = 0; m < 4; ++m) _Pragma("unroll") for (int k = 0; k < 2; ++k) dst[m][k] = *(const PG8_LAS bf16x8*)(lds + PG8_SA(b, h) + aoff + m * 2048 + k * 1024); } while (0)
; #define PG8_LDB(dst, b, h) do { _Pragma("unroll") for (int n = 0; n < 2; ++n) _Pragma("unroll") for (int k = 0; k < 2; ++k) dst[n][k] = *(const PG8_LAS bf16x8*)(lds + PG8_SB(b, h) + boff + n * 2048 + k * 1024); } while (0)
; #define PG8_MMA(ai, bj, At, Bt) do { __builtin_amdgcn_s_setprio(1); _Pragma("unroll") for (int m = 0; m < 4; ++m) _Pragma("unroll") for (int n = 0; n < 2; ++n) _Pragma("unroll") for (int k = 0; k < 2; ++k) \
;         acc[ai][bj][m][n] = __builtin_amdgcn_mfma_f32_16x16x32_bf16(Bt[n][k], At[m][k], acc[ai][bj][m][n], 0, 0, 0); __builtin_amdgcn_s_setprio(0); } while (0)
; #define PG8_WAIT_L(n) asm volatile("s_waitcnt lgkmcnt(" #n ")" ::: "memory")
; #define PG8_BAR __builtin_amdgcn_s_barrier()
; #define PG8_SCHED __builtin_amdgcn_sched_barrier(0)
; template <class Epi, class Sched>
; __device__ __forceinline__ void gemm_phase(PG8_LAS unsigned char* lds, const Gemm g, const Sched& S, const Epi& E) {
;     ...
;         for (int t = 0; t < nt; t += 2) {
;             const bool last = (t == nt - 2);
;             const char* a1 = cA + (size_t)(t + 1) * kstep;
;             const char* a2 = last ? nA : cA + (size_t)(t + 2) * kstep; const char* b2 = last ? nB : cB + (size_t)(t + 2) * kstep;
;             const char* a3 = a2 + kstep; const char* b3 = b2 + kstep;
;             if (last && has_next) S.a_ready(nxt);
;             PG8_LDB(B0, 0, 0); PG8_SCHED; PG8_LDA(At, 0, 0); PG8_STAGE(PG8_SA(1, 1), a1 + hstep, voffA);
;             PG8_WAIT_L(8); PG8_BAR; PG8_WAIT_L(0); PG8_MMA(0, 0, At, B0); PG8_BAR; PG8_SCHED;
;             PG8_LDB(B1, 0, 1); PG8_STAGE(PG8_SB(0, 0), b2, voffB);
;             PG8_BAR; PG8_WAIT_L(0); PG8_MMA(0, 1, At, B1); PG8_BAR;
;             PG8_LDA(At, 0, 1); PG8_STAGE(PG8_SA(0, 0), a2, voffA);
;             PG8_BAR; PG8_WAIT_L(0); PG8_MMA(1, 0, At, B0); PG8_BAR; PG8_SCHED;
.LBB0_137:
	s_add_u32 s14, s12, 0xfffc0080
	s_addc_u32 s15, s13, -1
	v_add_u32_e32 v154, 0x10000, v139
	ds_read_b128 v[142:145], v154
	ds_read_b128 v[146:149], v154 offset:1024
	ds_read_b128 v[150:153], v154 offset:2048
	ds_read_b128 v[154:157], v154 offset:3072
	s_cmp_eq_u32 s45, 12
	s_cselect_b32 s17, s7, s15
	s_cselect_b32 s16, s40, s14
	s_cselect_b32 s15, s5, s44
	s_cselect_b32 s14, s41, s43
	s_add_i32 m0, s1, 0xc000
	ds_read_b128 v[158:161], v141
	ds_read_b128 v[162:165], v141 offset:1024
	ds_read_b128 v[166:169], v141 offset:2048
	ds_read_b128 v[170:173], v141 offset:3072
	ds_read_b128 v[178:181], v141 offset:4096
	ds_read_b128 v[182:185], v141 offset:5120
	ds_read_b128 v[186:189], v141 offset:6144
	global_load_lds_dwordx4 v134, s[12:13]
	s_add_i32 m0, s1, 0xe000
	ds_read_b128 v[190:193], v141 offset:7168
	global_load_lds_dwordx4 v136, s[12:13]
	s_waitcnt lgkmcnt(8)
	s_barrier
	s_waitcnt lgkmcnt(7)
	v_mfma_f32_16x16x32_bf16 v[124:127], v[142:145], v[158:161], v[124:127]
	v_mfma_f32_16x16x32_bf16 v[120:123], v[150:153], v[158:161], v[120:123]
	s_waitcnt lgkmcnt(5)
	v_mfma_f32_16x16x32_bf16 v[116:119], v[142:145], v[166:169], v[116:119]
	v_mfma_f32_16x16x32_bf16 v[112:115], v[150:153], v[166:169], v[112:115]
	s_waitcnt lgkmcnt(3)
	v_mfma_f32_16x16x32_bf16 v[100:103], v[142:145], v[178:181], v[100:103]
	v_mfma_f32_16x16x32_bf16 v[96:99], v[150:153], v[178:181], v[96:99]
	s_waitcnt lgkmcnt(1)
	v_mfma_f32_16x16x32_bf16 v[84:87], v[142:145], v[186:189], v[84:87]
	v_mfma_f32_16x16x32_bf16 v[80:83], v[150:153], v[186:189], v[80:83]
	v_mfma_f32_16x16x32_bf16 v[124:127], v[146:149], v[162:165], v[124:127]
	v_mfma_f32_16x16x32_bf16 v[120:123], v[154:157], v[162:165], v[120:123]
	v_mfma_f32_16x16x32_bf16 v[116:119], v[146:149], v[170:173], v[116:119]
	v_mfma_f32_16x16x32_bf16 v[112:115], v[154:157], v[170:173], v[112:115]
	v_mfma_f32_16x16x32_bf16 v[100:103], v[146:149], v[182:185], v[100:103]
	v_mfma_f32_16x16x32_bf16 v[96:99], v[154:157], v[182:185], v[96:99]
	s_waitcnt lgkmcnt(0)
	v_mfma_f32_16x16x32_bf16 v[84:87], v[146:149], v[190:193], v[84:87]
	v_mfma_f32_16x16x32_bf16 v[80:83], v[154:157], v[190:193], v[80:83]
	s_barrier
	s_add_i32 s48, 0, 0x14000
	v_add_u32_e32 v174, 0x14000, v139
	ds_read_b128 v[194:197], v174
	ds_read_b128 v[198:201], v174 offset:1024
	s_add_u32 s98, s14, 0x80
	s_addc_u32 s99, s15, 0
	s_add_i32 m0, s20, 0x10000
	ds_read_b128 v[202:205], v174 offset:2048
	global_load_lds_dwordx4 v176, s[14:15]
	s_add_i32 m0, s20, 0x12000
	ds_read_b128 v[206:209], v174 offset:3072
	global_load_lds_dwordx4 v128, s[14:15]
	s_barrier
	s_waitcnt lgkmcnt(3)
	v_mfma_f32_16x16x32_bf16 v[108:111], v[194:197], v[158:161], v[108:111]
	s_waitcnt lgkmcnt(1)
	v_mfma_f32_16x16x32_bf16 v[104:107], v[202:205], v[158:161], v[104:107]
	v_mfma_f32_16x16x32_bf16 v[92:95], v[194:197], v[166:169], v[92:95]
	v_mfma_f32_16x16x32_bf16 v[88:91], v[202:205], v[166:169], v[88:91]
	v_mfma_f32_16x16x32_bf16 v[76:79], v[194:197], v[178:181], v[76:79]
	v_mfma_f32_16x16x32_bf16 v[72:75], v[202:205], v[178:181], v[72:75]
	v_mfma_f32_16x16x32_bf16 v[68:71], v[194:197], v[186:189], v[68:71]
	v_mfma_f32_16x16x32_bf16 v[64:67], v[202:205], v[186:189], v[64:67]
	v_mfma_f32_16x16x32_bf16 v[108:111], v[198:201], v[162:165], v[108:111]
	s_waitcnt lgkmcnt(0)
	v_mfma_f32_16x16x32_bf16 v[104:107], v[206:209], v[162:165], v[104:107]
	v_mfma_f32_16x16x32_bf16 v[92:95], v[198:201], v[170:173], v[92:95]
	v_mfma_f32_16x16x32_bf16 v[88:91], v[206:209], v[170:173], v[88:91]
	v_mfma_f32_16x16x32_bf16 v[76:79], v[198:201], v[182:185], v[76:79]
	v_mfma_f32_16x16x32_bf16 v[72:75], v[206:209], v[182:185], v[72:75]
	v_mfma_f32_16x16x32_bf16 v[68:71], v[198:201], v[190:193], v[68:71]
	v_mfma_f32_16x16x32_bf16 v[64:67], v[206:209], v[190:193], v[64:67]
	s_mov_b32 m0, s1
	s_add_u32 s100, s16, 0x80
	s_addc_u32 s101, s17, 0
	s_barrier
	ds_read_b128 v[158:161], v141 offset:16384
	ds_read_b128 v[162:165], v141 offset:17408
	ds_read_b128 v[166:169], v141 offset:18432
	ds_read_b128 v[170:173], v141 offset:19456
	ds_read_b128 v[178:181], v141 offset:20480
	ds_read_b128 v[182:185], v141 offset:21504
	ds_read_b128 v[186:189], v141 offset:22528
	global_load_lds_dwordx4 v132, s[16:17]
	s_mov_b32 m0, s22
	ds_read_b128 v[190:193], v141 offset:23552
	global_load_lds_dwordx4 v130, s[16:17]
	s_barrier
	s_waitcnt lgkmcnt(7)
	v_mfma_f32_16x16x32_bf16 v[60:63], v[142:145], v[158:161], v[60:63]
	v_mfma_f32_16x16x32_bf16 v[56:59], v[150:153], v[158:161], v[56:59]
	s_waitcnt lgkmcnt(5)
	v_mfma_f32_16x16x32_bf16 v[52:55], v[142:145], v[166:169], v[52:55]
	v_mfma_f32_16x16x32_bf16 v[48:51], v[150:153], v[166:169], v[48:51]
	s_waitcnt lgkmcnt(3)
	v_mfma_f32_16x16x32_bf16 v[36:39], v[142:145], v[178:181], v[36:39]
	v_mfma_f32_16x16x32_bf16 v[32:35], v[150:153], v[178:181], v[32:35]
	s_waitcnt lgkmcnt(1)
	v_mfma_f32_16x16x32_bf16 v[20:23], v[142:145], v[186:189], v[20:23]
	v_mfma_f32_16x16x32_bf16 v[16:19], v[150:153], v[186:189], v[16:19]
	v_mfma_f32_16x16x32_bf16 v[60:63], v[146:149], v[162:165], v[60:63]
	v_mfma_f32_16x16x32_bf16 v[56:59], v[154:157], v[162:165], v[56:59]
	v_mfma_f32_16x16x32_bf16 v[52:55], v[146:149], v[170:173], v[52:55]
	v_mfma_f32_16x16x32_bf16 v[48:51], v[154:157], v[170:173], v[48:51]
	v_mfma_f32_16x16x32_bf16 v[36:39], v[146:149], v[182:185], v[36:39]
	v_mfma_f32_16x16x32_bf16 v[32:35], v[154:157], v[182:185], v[32:35]
	s_waitcnt lgkmcnt(0)
	v_mfma_f32_16x16x32_bf16 v[20:23], v[146:149], v[190:193], v[20:23]
	v_mfma_f32_16x16x32_bf16 v[16:19], v[154:157], v[190:193], v[16:19]
	s_barrier
; #define PG8_STAGE(bufoff, gbase, voff) do { _Pragma("unroll") for (int _i = 0; _i < 2; ++_i) \
;         __builtin_amdgcn_global_load_lds((const unsigned*)((const char*)(gbase) + (voff)[_i]), (PG8_LAS unsigned*)(lds + (bufoff) + ldsw + _i * 8192), 16, 0, 0); } while (0)
; #define PG8_LDA(dst, b, h) do { _Pragma("unroll") for (int m = 0; m < 4; ++m) _Pragma("unroll") for (int k = 0; k < 2; ++k) dst[m][k] = *(const PG8_LAS bf16x8*)(lds + PG8_SA(b, h) + aoff + m * 2048 + k * 1024); } while (0)
; #define PG8_LDB(dst, b, h) do { _Pragma("unroll") for (int n = 0; n < 2; ++n) _Pragma("unroll") for (int k = 0; k < 2; ++k) dst[n][k] = *(const PG8_LAS bf16x8*)(lds + PG8_SB(b, h) + boff + n * 2048 + k * 1024); } while (0)
; #define PG8_MMA(ai, bj, At, Bt) do { __builtin_amdgcn_s_setprio(1); _Pragma("unroll") for (int m = 0; m < 4; ++m) _Pragma("unroll") for (int n = 0; n < 2; ++n) _Pragma("unroll") for (int k = 0; k < 2; ++k) \
;         acc[ai][bj][m][n] = __builtin_amdgcn_mfma_f32_16x16x32_bf16(Bt[n][k], At[m][k], acc[ai][bj][m][n], 0, 0, 0); __builtin_amdgcn_s_setprio(0); } while (0)
; #define PG8_WAIT_V(n) asm volatile("s_waitcnt vmcnt(" #n ")" ::: "memory")
; #define PG8_WAIT_L(n) asm volatile("s_waitcnt lgkmcnt(" #n ")" ::: "memory")
; #define PG8_BAR __builtin_amdgcn_s_barrier()
; #define PG8_SCHED __builtin_amdgcn_sched_barrier(0)
; template <class Epi, class Sched>
; __device__ __forceinline__ void gemm_phase(PG8_LAS unsigned char* lds, const Gemm g, const Sched& S, const Epi& E) {
;     ...
;             PG8_STAGE(PG8_SB(0, 1), b2 + hstep, voffB);
;             PG8_WAIT_V(6); PG8_BAR; PG8_MMA(1, 1, At, B1); PG8_BAR;
;             PG8_LDB(B0, 1, 0); PG8_SCHED; PG8_LDA(At, 1, 0); PG8_STAGE(PG8_SA(0, 1), a2 + hstep, voffA);
;             PG8_WAIT_L(8); PG8_BAR; PG8_WAIT_L(0); PG8_MMA(0, 0, At, B0); PG8_BAR; PG8_SCHED;
;             PG8_LDB(B1, 1, 1); PG8_STAGE(PG8_SB(1, 0), b3, voffB);
;             PG8_BAR; PG8_WAIT_L(0); PG8_MMA(0, 1, At, B1); PG8_BAR;
;             PG8_LDA(At, 1, 1); PG8_STAGE(PG8_SA(1, 0), a3, voffA);
;             PG8_BAR; PG8_WAIT_L(0); PG8_MMA(1, 0, At, B0); PG8_BAR; PG8_SCHED;
	s_add_u32 s46, s14, 0x40000
	s_addc_u32 s47, s15, 0
	s_add_i32 m0, s20, 0x14000
	s_nop 0
	global_load_lds_dwordx4 v176, s[46:47]
	s_add_i32 m0, s20, 0x16000
	s_nop 0
	global_load_lds_dwordx4 v128, s[46:47]
	s_waitcnt vmcnt(6)
	s_barrier
	v_mfma_f32_16x16x32_bf16 v[44:47], v[194:197], v[158:161], v[44:47]
	v_mfma_f32_16x16x32_bf16 v[40:43], v[202:205], v[158:161], v[40:43]
	v_mfma_f32_16x16x32_bf16 v[28:31], v[194:197], v[166:169], v[28:31]
	v_mfma_f32_16x16x32_bf16 v[24:27], v[202:205], v[166:169], v[24:27]
	v_mfma_f32_16x16x32_bf16 v[12:15], v[194:197], v[178:181], v[12:15]
	v_mfma_f32_16x16x32_bf16 v[8:11], v[202:205], v[178:181], v[8:11]
	v_mfma_f32_16x16x32_bf16 v[4:7], v[194:197], v[186:189], v[4:7]
	v_mfma_f32_16x16x32_bf16 v[0:3], v[202:205], v[186:189], v[0:3]
	v_mfma_f32_16x16x32_bf16 v[44:47], v[198:201], v[162:165], v[44:47]
	v_mfma_f32_16x16x32_bf16 v[40:43], v[206:209], v[162:165], v[40:43]
	v_mfma_f32_16x16x32_bf16 v[28:31], v[198:201], v[170:173], v[28:31]
	v_mfma_f32_16x16x32_bf16 v[24:27], v[206:209], v[170:173], v[24:27]
	v_mfma_f32_16x16x32_bf16 v[12:15], v[198:201], v[182:185], v[12:15]
	v_mfma_f32_16x16x32_bf16 v[8:11], v[206:209], v[182:185], v[8:11]
	v_mfma_f32_16x16x32_bf16 v[4:7], v[198:201], v[190:193], v[4:7]
	v_mfma_f32_16x16x32_bf16 v[0:3], v[206:209], v[190:193], v[0:3]
	v_add_u32_e32 v154, 0x18000, v139
	s_barrier
	ds_read_b128 v[142:145], v154
	ds_read_b128 v[146:149], v154 offset:1024
	ds_read_b128 v[150:153], v154 offset:2048
	ds_read_b128 v[154:157], v154 offset:3072
	s_add_u32 s16, s16, 0x40000
	s_addc_u32 s17, s17, 0
	s_mov_b32 m0, s23
	ds_read_b128 v[158:161], v141 offset:32768
	ds_read_b128 v[162:165], v141 offset:33792
	ds_read_b128 v[166:169], v141 offset:34816
	ds_read_b128 v[170:173], v141 offset:35840
	ds_read_b128 v[178:181], v141 offset:36864
	ds_read_b128 v[182:185], v141 offset:37888
	ds_read_b128 v[186:189], v141 offset:38912
	global_load_lds_dwordx4 v132, s[16:17]
	s_mov_b32 m0, s26
	ds_read_b128 v[190:193], v141 offset:39936
	global_load_lds_dwordx4 v130, s[16:17]
	s_waitcnt lgkmcnt(8)
	s_barrier
	s_waitcnt lgkmcnt(7)
	v_mfma_f32_16x16x32_bf16 v[124:127], v[142:145], v[158:161], v[124:127]
	v_mfma_f32_16x16x32_bf16 v[120:123], v[150:153], v[158:161], v[120:123]
	s_waitcnt lgkmcnt(5)
	v_mfma_f32_16x16x32_bf16 v[116:119], v[142:145], v[166:169], v[116:119]
	v_mfma_f32_16x16x32_bf16 v[112:115], v[150:153], v[166:169], v[112:115]
	s_waitcnt lgkmcnt(3)
	v_mfma_f32_16x16x32_bf16 v[100:103], v[142:145], v[178:181], v[100:103]
	v_mfma_f32_16x16x32_bf16 v[96:99], v[150:153], v[178:181], v[96:99]
	s_waitcnt lgkmcnt(1)
	v_mfma_f32_16x16x32_bf16 v[84:87], v[142:145], v[186:189], v[84:87]
	v_mfma_f32_16x16x32_bf16 v[80:83], v[150:153], v[186:189], v[80:83]
	v_mfma_f32_16x16x32_bf16 v[124:127], v[146:149], v[162:165], v[124:127]
	v_mfma_f32_16x16x32_bf16 v[120:123], v[154:157], v[162:165], v[120:123]
	v_mfma_f32_16x16x32_bf16 v[116:119], v[146:149], v[170:173], v[116:119]
	v_mfma_f32_16x16x32_bf16 v[112:115], v[154:157], v[170:173], v[112:115]
	v_mfma_f32_16x16x32_bf16 v[100:103], v[146:149], v[182:185], v[100:103]
	v_mfma_f32_16x16x32_bf16 v[96:99], v[154:157], v[182:185], v[96:99]
	s_waitcnt lgkmcnt(0)
	v_mfma_f32_16x16x32_bf16 v[84:87], v[146:149], v[190:193], v[84:87]
	v_mfma_f32_16x16x32_bf16 v[80:83], v[154:157], v[190:193], v[80:83]
	s_barrier
	v_add_u32_e32 v206, 0x1c000, v139
	s_add_i32 m0, s20, 0x18000
	ds_read_b128 v[194:197], v206
	ds_read_b128 v[198:201], v206 offset:1024
	ds_read_b128 v[202:205], v206 offset:2048
	global_load_lds_dwordx4 v176, s[98:99]
	s_add_i32 m0, s20, 0x1a000
	ds_read_b128 v[206:209], v206 offset:3072
	global_load_lds_dwordx4 v128, s[98:99]
	s_barrier
	s_waitcnt lgkmcnt(3)
	v_mfma_f32_16x16x32_bf16 v[108:111], v[194:197], v[158:161], v[108:111]
	s_waitcnt lgkmcnt(1)
	v_mfma_f32_16x16x32_bf16 v[104:107], v[202:205], v[158:161], v[104:107]
	v_mfma_f32_16x16x32_bf16 v[92:95], v[194:197], v[166:169], v[92:95]
	v_mfma_f32_16x16x32_bf16 v[88:91], v[202:205], v[166:169], v[88:91]
	v_mfma_f32_16x16x32_bf16 v[76:79], v[194:197], v[178:181], v[76:79]
	v_mfma_f32_16x16x32_bf16 v[72:75], v[202:205], v[178:181], v[72:75]
	v_mfma_f32_16x16x32_bf16 v[68:71], v[194:197], v[186:189], v[68:71]
	v_mfma_f32_16x16x32_bf16 v[64:67], v[202:205], v[186:189], v[64:67]
	v_mfma_f32_16x16x32_bf16 v[108:111], v[198:201], v[162:165], v[108:111]
	s_waitcnt lgkmcnt(0)
	v_mfma_f32_16x16x32_bf16 v[104:107], v[206:209], v[162:165], v[104:107]
	v_mfma_f32_16x16x32_bf16 v[92:95], v[198:201], v[170:173], v[92:95]
	v_mfma_f32_16x16x32_bf16 v[88:91], v[206:209], v[170:173], v[88:91]
	v_mfma_f32_16x16x32_bf16 v[76:79], v[198:201], v[182:185], v[76:79]
	v_mfma_f32_16x16x32_bf16 v[72:75], v[206:209], v[182:185], v[72:75]
	v_mfma_f32_16x16x32_bf16 v[68:71], v[198:201], v[190:193], v[68:71]
	v_mfma_f32_16x16x32_bf16 v[64:67], v[206:209], v[190:193], v[64:67]
	s_mov_b32 m0, s28
	s_barrier
	ds_read_b128 v[158:161], v141 offset:49152
	ds_read_b128 v[162:165], v141 offset:50176
	ds_read_b128 v[166:169], v141 offset:51200
	ds_read_b128 v[170:173], v141 offset:52224
	ds_read_b128 v[178:181], v141 offset:53248
	ds_read_b128 v[182:185], v141 offset:54272
	ds_read_b128 v[186:189], v141 offset:55296
	global_load_lds_dwordx4 v132, s[100:101]
	s_mov_b32 m0, s29
	ds_read_b128 v[190:193], v141 offset:56320
	global_load_lds_dwordx4 v130, s[100:101]
	s_barrier
; #define PG8_STAGE(bufoff, gbase, voff) do { _Pragma("unroll") for (int _i = 0; _i < 2; ++_i) \
;         __builtin_amdgcn_global_load_lds((const unsigned*)((const char*)(gbase) + (voff)[_i]), (PG8_LAS unsigned*)(lds + (bufoff) + ldsw + _i * 8192), 16, 0, 0); } while (0)
; #define PG8_MMA(ai, bj, At, Bt) do { __builtin_amdgcn_s_setprio(1); _Pragma("unroll") for (int m = 0; m < 4; ++m) _Pragma("unroll") for (int n = 0; n < 2; ++n) _Pragma("unroll") for (int k = 0; k < 2; ++k) \
;         acc[ai][bj][m][n] = __builtin_amdgcn_mfma_f32_16x16x32_bf16(Bt[n][k], At[m][k], acc[ai][bj][m][n], 0, 0, 0); __builtin_amdgcn_s_setprio(0); } while (0)
; #define PG8_WAIT_V(n) asm volatile("s_waitcnt vmcnt(" #n ")" ::: "memory")
; #define PG8_WAIT_L(n) asm volatile("s_waitcnt lgkmcnt(" #n ")" ::: "memory")
; #define PG8_BAR __builtin_amdgcn_s_barrier()
; #define PG8_SCHED __builtin_amdgcn_sched_barrier(0)
; template <class Epi, class Sched>
; __device__ __forceinline__ void gemm_phase(PG8_LAS unsigned char* lds, const Gemm g, const Sched& S, const Epi& E) {
;     ...
;             PG8_BAR; PG8_WAIT_L(0); PG8_MMA(1, 0, At, B0); PG8_BAR; PG8_SCHED;
;             PG8_STAGE(PG8_SB(1, 1), b3 + hstep, voffB);
;             PG8_WAIT_V(6); PG8_BAR; PG8_MMA(1, 1, At, B1); PG8_BAR;
;         }
	s_waitcnt lgkmcnt(7)
	v_mfma_f32_16x16x32_bf16 v[60:63], v[142:145], v[158:161], v[60:63]
	v_mfma_f32_16x16x32_bf16 v[56:59], v[150:153], v[158:161], v[56:59]
	s_waitcnt lgkmcnt(5)
	v_mfma_f32_16x16x32_bf16 v[52:55], v[142:145], v[166:169], v[52:55]
	v_mfma_f32_16x16x32_bf16 v[48:51], v[150:153], v[166:169], v[48:51]
	s_waitcnt lgkmcnt(3)
	v_mfma_f32_16x16x32_bf16 v[36:39], v[142:145], v[178:181], v[36:39]
	v_mfma_f32_16x16x32_bf16 v[32:35], v[150:153], v[178:181], v[32:35]
	s_waitcnt lgkmcnt(1)
	v_mfma_f32_16x16x32_bf16 v[20:23], v[142:145], v[186:189], v[20:23]
	v_mfma_f32_16x16x32_bf16 v[16:19], v[150:153], v[186:189], v[16:19]
	v_mfma_f32_16x16x32_bf16 v[60:63], v[146:149], v[162:165], v[60:63]
	v_mfma_f32_16x16x32_bf16 v[56:59], v[154:157], v[162:165], v[56:59]
	v_mfma_f32_16x16x32_bf16 v[52:55], v[146:149], v[170:173], v[52:55]
	v_mfma_f32_16x16x32_bf16 v[48:51], v[154:157], v[170:173], v[48:51]
	v_mfma_f32_16x16x32_bf16 v[36:39], v[146:149], v[182:185], v[36:39]
	v_mfma_f32_16x16x32_bf16 v[32:35], v[154:157], v[182:185], v[32:35]
	s_waitcnt lgkmcnt(0)
	v_mfma_f32_16x16x32_bf16 v[20:23], v[146:149], v[190:193], v[20:23]
	v_mfma_f32_16x16x32_bf16 v[16:19], v[154:157], v[190:193], v[16:19]
	s_barrier
	s_add_u32 s14, s14, 0x40080
	s_addc_u32 s15, s15, 0
	s_add_i32 m0, s20, 0x1c000
	s_nop 0
	global_load_lds_dwordx4 v176, s[14:15]
	s_add_i32 m0, s20, 0x1e000
	s_nop 0
	global_load_lds_dwordx4 v128, s[14:15]
	s_waitcnt vmcnt(6)
	s_barrier
	v_mfma_f32_16x16x32_bf16 v[44:47], v[194:197], v[158:161], v[44:47]
	v_mfma_f32_16x16x32_bf16 v[40:43], v[202:205], v[158:161], v[40:43]
	v_mfma_f32_16x16x32_bf16 v[28:31], v[194:197], v[166:169], v[28:31]
	v_mfma_f32_16x16x32_bf16 v[24:27], v[202:205], v[166:169], v[24:27]
	v_mfma_f32_16x16x32_bf16 v[12:15], v[194:197], v[178:181], v[12:15]
	v_mfma_f32_16x16x32_bf16 v[8:11], v[202:205], v[178:181], v[8:11]
	v_mfma_f32_16x16x32_bf16 v[4:7], v[194:197], v[186:189], v[4:7]
	v_mfma_f32_16x16x32_bf16 v[0:3], v[202:205], v[186:189], v[0:3]
	v_mfma_f32_16x16x32_bf16 v[44:47], v[198:201], v[162:165], v[44:47]
	v_mfma_f32_16x16x32_bf16 v[40:43], v[206:209], v[162:165], v[40:43]
	v_mfma_f32_16x16x32_bf16 v[28:31], v[198:201], v[170:173], v[28:31]
	v_mfma_f32_16x16x32_bf16 v[24:27], v[206:209], v[170:173], v[24:27]
	v_mfma_f32_16x16x32_bf16 v[12:15], v[198:201], v[182:185], v[12:15]
	v_mfma_f32_16x16x32_bf16 v[8:11], v[206:209], v[182:185], v[8:11]
	v_mfma_f32_16x16x32_bf16 v[4:7], v[198:201], v[190:193], v[4:7]
	v_mfma_f32_16x16x32_bf16 v[0:3], v[206:209], v[190:193], v[0:3]
	s_add_i32 s45, s45, 2
	s_add_u32 s12, s12, 0x100
	s_addc_u32 s13, s13, 0
	s_add_u32 s43, s43, 0x100
	s_addc_u32 s44, s44, 0
	s_cmp_gt_u32 s45, 13
	s_barrier
	s_cbranch_scc0 .LBB0_137
; __device__ __forceinline__ unsigned cvtpk(float lo, float hi) { const f32x2 v = (f32x2){lo, hi}; const bf16v2 b = __builtin_convertvector(v, bf16v2); return __builtin_bit_cast(unsigned, b); }
; template <class Epi, class Sched>
; __device__ __forceinline__ void gemm_phase(PG8_LAS unsigned char* lds, const Gemm g, const Sched& S, const Epi& E) {
;     ...
;         if constexpr (!Epi::AFTER_DRAIN) { E(acc, cur, wr, wc, fr, fq); S.done(cur); }
;         if (!has_next) break;
; #pragma unroll
;         for (int a = 0; a < 2; ++a)
; #pragma unroll
;             for (int b = 0; b < 2; ++b)
; #pragma unroll
;                 for (int m = 0; m < 4; ++m)
; #pragma unroll
;                     for (int n = 0; n < 2; ++n) acc[a][b][m][n] = (f32x4){0.f, 0.f, 0.f, 0.f};
;         cur = nxt; cA = nA; cB = nB; ++ui;
;     __device__ __forceinline__ void operator()(const f32x4 (&acc)[2][2][4][2], const pg8::Unit& u, int wr, int wc, int fr, int fq) const {
;         const int row0 = u.pm * 256 + wr * 64 + fr, col0 = u.pn * 256 + wc * 32 + 8 * fq;
; #pragma unroll
;         for (int ai = 0; ai < 2; ++ai)
; #pragma unroll
;             for (int m = 0; m < 4; ++m) { bf16_t* rowp = O + (size_t)(row0 + ai * 128 + m * 16) * ldc + col0;
; #pragma unroll
;                 for (int bj = 0; bj < 2; ++bj) { const f32x4 v0 = acc[ai][bj][m][0], v1 = acc[ai][bj][m][1];
;                     u32x4 w; w.x = cvtpk(v0[0], v0[1]); w.y = cvtpk(v0[2], v0[3]); w.z = cvtpk(v1[0], v1[1]); w.w = cvtpk(v1[2], v1[3]);
;                     *(u32x4*)(rowp + bj * 128) = w; } }
;     }
	v_lshl_add_u32 v142, s0, 8, v138
	v_lshl_or_b32 v144, s34, 8, v140
	v_ashrrev_i32_e32 v143, 31, v142
	v_readlane_b32 s12, v253, 18
	v_ashrrev_i32_e32 v145, 31, v144
	v_lshlrev_b64 v[146:147], 11, v[142:143]
	v_readlane_b32 s13, v253, 19
	v_cvt_pk_bf16_f32 v108, v108, v109
	v_cvt_pk_bf16_f32 v109, v110, v111
	v_cvt_pk_bf16_f32 v110, v104, v105
	v_or_b32_e32 v104, 16, v142
	v_cvt_pk_bf16_f32 v92, v92, v93
	v_cvt_pk_bf16_f32 v93, v94, v95
	v_cvt_pk_bf16_f32 v94, v88, v89
	v_or_b32_e32 v88, 32, v142
	v_cvt_pk_bf16_f32 v76, v76, v77
	v_cvt_pk_bf16_f32 v77, v78, v79
	v_cvt_pk_bf16_f32 v78, v72, v73
	v_or_b32_e32 v72, 48, v142
	v_lshl_add_u64 v[146:147], s[12:13], 0, v[146:147]
	v_lshlrev_b64 v[144:145], 1, v[144:145]
	v_ashrrev_i32_e32 v105, 31, v104
	v_ashrrev_i32_e32 v89, 31, v88
	v_ashrrev_i32_e32 v73, 31, v72
	v_lshl_add_u64 v[146:147], v[146:147], 0, v[144:145]
	v_lshlrev_b64 v[104:105], 11, v[104:105]
	v_lshlrev_b64 v[88:89], 11, v[88:89]
	v_lshlrev_b64 v[72:73], 11, v[72:73]
	v_lshl_add_u64 v[104:105], s[12:13], 0, v[104:105]
	v_lshl_add_u64 v[88:89], s[12:13], 0, v[88:89]
	v_lshl_add_u64 v[72:73], s[12:13], 0, v[72:73]
	s_mov_b64 s[12:13], 0x40000
	v_cvt_pk_bf16_f32 v60, v60, v61
	v_cvt_pk_bf16_f32 v61, v62, v63
	v_cvt_pk_bf16_f32 v62, v56, v57
	v_add_co_u32_e32 v56, vcc, s2, v146
	v_cvt_pk_bf16_f32 v68, v68, v69
	v_cvt_pk_bf16_f32 v69, v70, v71
	v_cvt_pk_bf16_f32 v70, v64, v65
	v_lshl_add_u64 v[64:65], v[146:147], 0, s[12:13]
	v_addc_co_u32_e32 v57, vcc, 0, v147, vcc
	v_cvt_pk_bf16_f32 v44, v44, v45
	v_cvt_pk_bf16_f32 v45, v46, v47
	v_cvt_pk_bf16_f32 v46, v40, v41
	v_cvt_pk_bf16_f32 v47, v42, v43
	s_mov_b32 s0, 0x48000
	global_store_dwordx4 v[64:65], v[44:47], off offset:256
	s_mov_b64 s[12:13], 0x48000
	v_cvt_pk_bf16_f32 v28, v28, v29
	v_add_co_u32_e32 v46, vcc, s0, v146
	v_lshl_add_u64 v[44:45], v[146:147], 0, s[12:13]
	s_nop 0
	v_addc_co_u32_e32 v47, vcc, 0, v147, vcc
	v_cvt_pk_bf16_f32 v29, v30, v31
	v_cvt_pk_bf16_f32 v30, v24, v25
	v_cvt_pk_bf16_f32 v31, v26, v27
	s_mov_b32 s0, 0x50000
	global_store_dwordx4 v[44:45], v[28:31], off offset:256
	s_mov_b64 s[12:13], 0x50000
	v_cvt_pk_bf16_f32 v111, v106, v107
	v_add_co_u32_e32 v30, vcc, s0, v146
	v_lshl_add_u64 v[28:29], v[146:147], 0, s[12:13]
	s_nop 0
	v_addc_co_u32_e32 v31, vcc, 0, v147, vcc
	v_cvt_pk_bf16_f32 v12, v12, v13
	v_cvt_pk_bf16_f32 v13, v14, v15
	v_cvt_pk_bf16_f32 v14, v8, v9
	v_cvt_pk_bf16_f32 v15, v10, v11
	s_mov_b32 s0, 0x58000
	global_store_dwordx4 v[146:147], v[108:111], off offset:256
	v_cvt_pk_bf16_f32 v95, v90, v91
	global_store_dwordx4 v[28:29], v[12:15], off offset:256
	v_lshl_add_u64 v[108:109], v[104:105], 0, v[144:145]
	global_store_dwordx4 v[108:109], v[92:95], off offset:256
	v_add_co_u32_e32 v14, vcc, s0, v146
	s_nop 0
	v_lshl_add_u64 v[92:93], v[88:89], 0, v[144:145]
	v_cvt_pk_bf16_f32 v79, v74, v75
	s_mov_b64 s[12:13], 0x58000
	v_addc_co_u32_e32 v15, vcc, 0, v147, vcc
	v_cvt_pk_bf16_f32 v124, v124, v125
	v_cvt_pk_bf16_f32 v125, v126, v127
	v_cvt_pk_bf16_f32 v126, v120, v121
	v_cvt_pk_bf16_f32 v127, v122, v123
	v_cvt_pk_bf16_f32 v104, v116, v117
	v_cvt_pk_bf16_f32 v105, v118, v119
	v_cvt_pk_bf16_f32 v106, v112, v113
	v_cvt_pk_bf16_f32 v107, v114, v115
	v_cvt_pk_bf16_f32 v88, v100, v101
	v_cvt_pk_bf16_f32 v89, v102, v103
	v_cvt_pk_bf16_f32 v90, v96, v97
	v_cvt_pk_bf16_f32 v91, v98, v99
	global_store_dwordx4 v[92:93], v[76:79], off offset:256
	v_cvt_pk_bf16_f32 v74, v80, v81
	v_cvt_pk_bf16_f32 v75, v82, v83
	v_lshl_add_u64 v[76:77], v[72:73], 0, v[144:145]
	v_cvt_pk_bf16_f32 v72, v84, v85
	v_cvt_pk_bf16_f32 v73, v86, v87
	v_cvt_pk_bf16_f32 v71, v66, v67
	v_cvt_pk_bf16_f32 v63, v58, v59
	v_cvt_pk_bf16_f32 v40, v52, v53
	v_cvt_pk_bf16_f32 v41, v54, v55
	v_cvt_pk_bf16_f32 v42, v48, v49
	v_cvt_pk_bf16_f32 v43, v50, v51
	v_cvt_pk_bf16_f32 v24, v36, v37
	v_cvt_pk_bf16_f32 v25, v38, v39
	v_cvt_pk_bf16_f32 v26, v32, v33
	v_cvt_pk_bf16_f32 v27, v34, v35
	v_lshl_add_u64 v[12:13], v[146:147], 0, s[12:13]
	v_cvt_pk_bf16_f32 v8, v20, v21
	v_cvt_pk_bf16_f32 v9, v22, v23
	v_cvt_pk_bf16_f32 v10, v16, v17
	v_cvt_pk_bf16_f32 v11, v18, v19
	v_cvt_pk_bf16_f32 v4, v4, v5
	v_cvt_pk_bf16_f32 v5, v6, v7
	v_cvt_pk_bf16_f32 v6, v0, v1
	v_cvt_pk_bf16_f32 v7, v2, v3
	s_and_b64 vcc, exec, s[38:39]
	s_mov_b32 s34, s4
	s_mov_b32 s0, s6
	s_mov_b64 s[14:15], s[10:11]
	s_mov_b64 s[12:13], s[8:9]
	global_store_dwordx4 v[146:147], v[124:127], off
	global_store_dwordx4 v[108:109], v[104:107], off
	global_store_dwordx4 v[92:93], v[88:91], off
	global_store_dwordx4 v[76:77], v[72:75], off
	global_store_dwordx4 v[76:77], v[68:71], off offset:256
	global_store_dwordx4 v[56:57], v[60:63], off
	global_store_dwordx4 v[46:47], v[40:43], off
	global_store_dwordx4 v[30:31], v[24:27], off
	global_store_dwordx4 v[14:15], v[8:11], off
	global_store_dwordx4 v[12:13], v[4:7], off offset:256
	s_cbranch_vccz .LBB0_134
	s_waitcnt vmcnt(0)
	v_readlane_b32 s22, v255, 14
	s_cmpk_gt_u32 s19, 0xff
	v_readlane_b32 s23, v255, 15
	s_mov_b64 s[28:29], s[54:55]
	s_cbranch_scc1 .LBB0_141
	s_barrier

; #define PG8_STAGE(bufoff, gbase, voff) do { _Pragma("unroll") for (int _i = 0; _i < 2; ++_i) \
;         __builtin_amdgcn_global_load_lds((const unsigned*)((const char*)(gbase) + (voff)[_i]), (PG8_LAS unsigned*)(lds + (bufoff) + ldsw + _i * 8192), 16, 0, 0); } while (0)
; #define PG8_LDA(dst, b, h) do { _Pragma("unroll") for (int m = 0; m < 4; ++m) _Pragma("unroll") for (int k = 0; k < 2; ++k) dst[m][k] = *(const PG8_LAS bf16x8*)(lds + PG8_SA(b, h) + aoff + m * 2048 + k * 1024); } while (0)
; #define PG8_LDB(dst, b, h) do { _Pragma("unroll") for (int n = 0; n < 2; ++n) _Pragma("unroll") for (int k = 0; k < 2; ++k) dst[n][k] = *(const PG8_LAS bf16x8*)(lds + PG8_SB(b, h) + boff + n * 2048 + k * 1024); } while (0)
; #define PG8_MMA(ai, bj, At, Bt) do { __builtin_amdgcn_s_setprio(1); _Pragma("unroll") for (int m = 0; m < 4; ++m) _Pragma("unroll") for (int n = 0; n < 2; ++n) _Pragma("unroll") for (int k = 0; k < 2; ++k) \
;         acc[ai][bj][m][n] = __builtin_amdgcn_mfma_f32_16x16x32_bf16(Bt[n][k], At[m][k], acc[ai][bj][m][n], 0, 0, 0); __builtin_amdgcn_s_setprio(0); } while (0)
; #define PG8_WAIT_L(n) asm volatile("s_waitcnt lgkmcnt(" #n ")" ::: "memory")
; #define PG8_BAR __builtin_amdgcn_s_barrier()
; #define PG8_SCHED __builtin_amdgcn_sched_barrier(0)
; template <class Epi, class Sched>
; __device__ __forceinline__ void gemm_phase(PG8_LAS unsigned char* lds, const Gemm g, const Sched& S, const Epi& E) {
;     ...
;         for (int t = 0; t < nt; t += 2) {
;             const bool last = (t == nt - 2);
;             const char* a1 = cA + (size_t)(t + 1) * kstep;
;             const char* a2 = last ? nA : cA + (size_t)(t + 2) * kstep; const char* b2 = last ? nB : cB + (size_t)(t + 2) * kstep;
;             const char* a3 = a2 + kstep; const char* b3 = b2 + kstep;
;             if (last && has_next) S.a_ready(nxt);
;             PG8_LDB(B0, 0, 0); PG8_SCHED; PG8_LDA(At, 0, 0); PG8_STAGE(PG8_SA(1, 1), a1 + hstep, voffA);
;             PG8_WAIT_L(8); PG8_BAR; PG8_WAIT_L(0); PG8_MMA(0, 0, At, B0); PG8_BAR; PG8_SCHED;
;             PG8_LDB(B1, 0, 1); PG8_STAGE(PG8_SB(0, 0), b2, voffB);
;             PG8_BAR; PG8_WAIT_L(0); PG8_MMA(0, 1, At, B1); PG8_BAR;
;             PG8_LDA(At, 0, 1); PG8_STAGE(PG8_SA(0, 0), a2, voffA);
;             PG8_BAR; PG8_WAIT_L(0); PG8_MMA(1, 0, At, B0); PG8_BAR; PG8_SCHED;
.LBB0_358:
	s_add_u32 s14, s12, 0xfffc0080
	s_addc_u32 s15, s13, -1
	v_add_u32_e32 v154, 0x10000, v139
	ds_read_b128 v[142:145], v154
	ds_read_b128 v[146:149], v154 offset:1024
	ds_read_b128 v[150:153], v154 offset:2048
	ds_read_b128 v[154:157], v154 offset:3072
	s_cmp_eq_u32 s45, 12
	s_cselect_b32 s17, s7, s15
	s_cselect_b32 s16, s40, s14
	s_cselect_b32 s15, s5, s44
	s_cselect_b32 s14, s41, s43
	s_add_i32 m0, s1, 0xc000
	ds_read_b128 v[158:161], v141
	ds_read_b128 v[162:165], v141 offset:1024
	ds_read_b128 v[166:169], v141 offset:2048
	ds_read_b128 v[170:173], v141 offset:3072
	ds_read_b128 v[182:185], v141 offset:4096
	ds_read_b128 v[190:193], v141 offset:5120
	ds_read_b128 v[194:197], v141 offset:6144
	global_load_lds_dwordx4 v134, s[12:13]
	s_add_i32 m0, s1, 0xe000
	ds_read_b128 v[198:201], v141 offset:7168
	global_load_lds_dwordx4 v136, s[12:13]
	s_waitcnt lgkmcnt(8)
	s_barrier
	s_waitcnt lgkmcnt(7)
	v_mfma_f32_16x16x32_bf16 v[124:127], v[142:145], v[158:161], v[124:127]
	v_mfma_f32_16x16x32_bf16 v[120:123], v[150:153], v[158:161], v[120:123]
	s_waitcnt lgkmcnt(5)
	v_mfma_f32_16x16x32_bf16 v[116:119], v[142:145], v[166:169], v[116:119]
	v_mfma_f32_16x16x32_bf16 v[112:115], v[150:153], v[166:169], v[112:115]
	s_waitcnt lgkmcnt(3)
	v_mfma_f32_16x16x32_bf16 v[100:103], v[142:145], v[182:185], v[100:103]
	v_mfma_f32_16x16x32_bf16 v[96:99], v[150:153], v[182:185], v[96:99]
	s_waitcnt lgkmcnt(1)
	v_mfma_f32_16x16x32_bf16 v[84:87], v[142:145], v[194:197], v[84:87]
	v_mfma_f32_16x16x32_bf16 v[80:83], v[150:153], v[194:197], v[80:83]
	v_mfma_f32_16x16x32_bf16 v[124:127], v[146:149], v[162:165], v[124:127]
	v_mfma_f32_16x16x32_bf16 v[120:123], v[154:157], v[162:165], v[120:123]
	v_mfma_f32_16x16x32_bf16 v[116:119], v[146:149], v[170:173], v[116:119]
	v_mfma_f32_16x16x32_bf16 v[112:115], v[154:157], v[170:173], v[112:115]
	v_mfma_f32_16x16x32_bf16 v[100:103], v[146:149], v[190:193], v[100:103]
	v_mfma_f32_16x16x32_bf16 v[96:99], v[154:157], v[190:193], v[96:99]
	s_waitcnt lgkmcnt(0)
	v_mfma_f32_16x16x32_bf16 v[84:87], v[146:149], v[198:201], v[84:87]
	v_mfma_f32_16x16x32_bf16 v[80:83], v[154:157], v[198:201], v[80:83]
	s_barrier
	s_add_i32 s48, 0, 0x14000
	v_add_u32_e32 v174, 0x14000, v139
	ds_read_b128 v[202:205], v174
	ds_read_b128 v[206:209], v174 offset:1024
	s_add_u32 s98, s14, 0x80
	s_addc_u32 s99, s15, 0
	s_add_i32 m0, s20, 0x10000
	ds_read_b128 v[210:213], v174 offset:2048
	global_load_lds_dwordx4 v176, s[14:15]
	s_add_i32 m0, s20, 0x12000
	ds_read_b128 v[214:217], v174 offset:3072
	global_load_lds_dwordx4 v128, s[14:15]
	s_barrier
	s_waitcnt lgkmcnt(3)
	v_mfma_f32_16x16x32_bf16 v[108:111], v[202:205], v[158:161], v[108:111]
	s_waitcnt lgkmcnt(1)
	v_mfma_f32_16x16x32_bf16 v[104:107], v[210:213], v[158:161], v[104:107]
	v_mfma_f32_16x16x32_bf16 v[92:95], v[202:205], v[166:169], v[92:95]
	v_mfma_f32_16x16x32_bf16 v[88:91], v[210:213], v[166:169], v[88:91]
	v_mfma_f32_16x16x32_bf16 v[76:79], v[202:205], v[182:185], v[76:79]
	v_mfma_f32_16x16x32_bf16 v[72:75], v[210:213], v[182:185], v[72:75]
	v_mfma_f32_16x16x32_bf16 v[68:71], v[202:205], v[194:197], v[68:71]
	v_mfma_f32_16x16x32_bf16 v[64:67], v[210:213], v[194:197], v[64:67]
	v_mfma_f32_16x16x32_bf16 v[108:111], v[206:209], v[162:165], v[108:111]
	s_waitcnt lgkmcnt(0)
	v_mfma_f32_16x16x32_bf16 v[104:107], v[214:217], v[162:165], v[104:107]
	v_mfma_f32_16x16x32_bf16 v[92:95], v[206:209], v[170:173], v[92:95]
	v_mfma_f32_16x16x32_bf16 v[88:91], v[214:217], v[170:173], v[88:91]
	v_mfma_f32_16x16x32_bf16 v[76:79], v[206:209], v[190:193], v[76:79]
	v_mfma_f32_16x16x32_bf16 v[72:75], v[214:217], v[190:193], v[72:75]
	v_mfma_f32_16x16x32_bf16 v[68:71], v[206:209], v[198:201], v[68:71]
	v_mfma_f32_16x16x32_bf16 v[64:67], v[214:217], v[198:201], v[64:67]
	s_mov_b32 m0, s1
	s_add_u32 s100, s16, 0x80
	s_addc_u32 s101, s17, 0
	s_barrier
	ds_read_b128 v[158:161], v141 offset:16384
	ds_read_b128 v[162:165], v141 offset:17408
	ds_read_b128 v[166:169], v141 offset:18432
	ds_read_b128 v[170:173], v141 offset:19456
	ds_read_b128 v[182:185], v141 offset:20480
	ds_read_b128 v[190:193], v141 offset:21504
	ds_read_b128 v[194:197], v141 offset:22528
	global_load_lds_dwordx4 v132, s[16:17]
	s_mov_b32 m0, s22
	ds_read_b128 v[198:201], v141 offset:23552
	global_load_lds_dwordx4 v130, s[16:17]
	s_barrier
	s_waitcnt lgkmcnt(7)
	v_mfma_f32_16x16x32_bf16 v[60:63], v[142:145], v[158:161], v[60:63]
	v_mfma_f32_16x16x32_bf16 v[56:59], v[150:153], v[158:161], v[56:59]
	s_waitcnt lgkmcnt(5)
	v_mfma_f32_16x16x32_bf16 v[52:55], v[142:145], v[166:169], v[52:55]
	v_mfma_f32_16x16x32_bf16 v[48:51], v[150:153], v[166:169], v[48:51]
	s_waitcnt lgkmcnt(3)
	v_mfma_f32_16x16x32_bf16 v[36:39], v[142:145], v[182:185], v[36:39]
	v_mfma_f32_16x16x32_bf16 v[32:35], v[150:153], v[182:185], v[32:35]
	s_waitcnt lgkmcnt(1)
	v_mfma_f32_16x16x32_bf16 v[20:23], v[142:145], v[194:197], v[20:23]
	v_mfma_f32_16x16x32_bf16 v[16:19], v[150:153], v[194:197], v[16:19]
	v_mfma_f32_16x16x32_bf16 v[60:63], v[146:149], v[162:165], v[60:63]
	v_mfma_f32_16x16x32_bf16 v[56:59], v[154:157], v[162:165], v[56:59]
	v_mfma_f32_16x16x32_bf16 v[52:55], v[146:149], v[170:173], v[52:55]
	v_mfma_f32_16x16x32_bf16 v[48:51], v[154:157], v[170:173], v[48:51]
	v_mfma_f32_16x16x32_bf16 v[36:39], v[146:149], v[190:193], v[36:39]
	v_mfma_f32_16x16x32_bf16 v[32:35], v[154:157], v[190:193], v[32:35]
	s_waitcnt lgkmcnt(0)
	v_mfma_f32_16x16x32_bf16 v[20:23], v[146:149], v[198:201], v[20:23]
	v_mfma_f32_16x16x32_bf16 v[16:19], v[154:157], v[198:201], v[16:19]
	s_barrier
; #define PG8_STAGE(bufoff, gbase, voff) do { _Pragma("unroll") for (int _i = 0; _i < 2; ++_i) \
;         __builtin_amdgcn_global_load_lds((const unsigned*)((const char*)(gbase) + (voff)[_i]), (PG8_LAS unsigned*)(lds + (bufoff) + ldsw + _i * 8192), 16, 0, 0); } while (0)
; #define PG8_LDA(dst, b, h) do { _Pragma("unroll") for (int m = 0; m < 4; ++m) _Pragma("unroll") for (int k = 0; k < 2; ++k) dst[m][k] = *(const PG8_LAS bf16x8*)(lds + PG8_SA(b, h) + aoff + m * 2048 + k * 1024); } while (0)
; #define PG8_LDB(dst, b, h) do { _Pragma("unroll") for (int n = 0; n < 2; ++n) _Pragma("unroll") for (int k = 0; k < 2; ++k) dst[n][k] = *(const PG8_LAS bf16x8*)(lds + PG8_SB(b, h) + boff + n * 2048 + k * 1024); } while (0)
; #define PG8_MMA(ai, bj, At, Bt) do { __builtin_amdgcn_s_setprio(1); _Pragma("unroll") for (int m = 0; m < 4; ++m) _Pragma("unroll") for (int n = 0; n < 2; ++n) _Pragma("unroll") for (int k = 0; k < 2; ++k) \
;         acc[ai][bj][m][n] = __builtin_amdgcn_mfma_f32_16x16x32_bf16(Bt[n][k], At[m][k], acc[ai][bj][m][n], 0, 0, 0); __builtin_amdgcn_s_setprio(0); } while (0)
; #define PG8_WAIT_V(n) asm volatile("s_waitcnt vmcnt(" #n ")" ::: "memory")
; #define PG8_WAIT_L(n) asm volatile("s_waitcnt lgkmcnt(" #n ")" ::: "memory")
; #define PG8_BAR __builtin_amdgcn_s_barrier()
; #define PG8_SCHED __builtin_amdgcn_sched_barrier(0)
; template <class Epi, class Sched>
; __device__ __forceinline__ void gemm_phase(PG8_LAS unsigned char* lds, const Gemm g, const Sched& S, const Epi& E) {
;     ...
;             PG8_STAGE(PG8_SB(0, 1), b2 + hstep, voffB);
;             PG8_WAIT_V(6); PG8_BAR; PG8_MMA(1, 1, At, B1); PG8_BAR;
;             PG8_LDB(B0, 1, 0); PG8_SCHED; PG8_LDA(At, 1, 0); PG8_STAGE(PG8_SA(0, 1), a2 + hstep, voffA);
;             PG8_WAIT_L(8); PG8_BAR; PG8_WAIT_L(0); PG8_MMA(0, 0, At, B0); PG8_BAR; PG8_SCHED;
;             PG8_LDB(B1, 1, 1); PG8_STAGE(PG8_SB(1, 0), b3, voffB);
;             PG8_BAR; PG8_WAIT_L(0); PG8_MMA(0, 1, At, B1); PG8_BAR;
;             PG8_LDA(At, 1, 1); PG8_STAGE(PG8_SA(1, 0), a3, voffA);
;             PG8_BAR; PG8_WAIT_L(0); PG8_MMA(1, 0, At, B0); PG8_BAR; PG8_SCHED;
	s_add_u32 s46, s14, 0x40000
	s_addc_u32 s47, s15, 0
	s_add_i32 m0, s20, 0x14000
	s_nop 0
	global_load_lds_dwordx4 v176, s[46:47]
	s_add_i32 m0, s20, 0x16000
	s_nop 0
	global_load_lds_dwordx4 v128, s[46:47]
	s_waitcnt vmcnt(6)
	s_barrier
	v_mfma_f32_16x16x32_bf16 v[44:47], v[202:205], v[158:161], v[44:47]
	v_mfma_f32_16x16x32_bf16 v[40:43], v[210:213], v[158:161], v[40:43]
	v_mfma_f32_16x16x32_bf16 v[28:31], v[202:205], v[166:169], v[28:31]
	v_mfma_f32_16x16x32_bf16 v[24:27], v[210:213], v[166:169], v[24:27]
	v_mfma_f32_16x16x32_bf16 v[12:15], v[202:205], v[182:185], v[12:15]
	v_mfma_f32_16x16x32_bf16 v[8:11], v[210:213], v[182:185], v[8:11]
	v_mfma_f32_16x16x32_bf16 v[4:7], v[202:205], v[194:197], v[4:7]
	v_mfma_f32_16x16x32_bf16 v[0:3], v[210:213], v[194:197], v[0:3]
	v_mfma_f32_16x16x32_bf16 v[44:47], v[206:209], v[162:165], v[44:47]
	v_mfma_f32_16x16x32_bf16 v[40:43], v[214:217], v[162:165], v[40:43]
	v_mfma_f32_16x16x32_bf16 v[28:31], v[206:209], v[170:173], v[28:31]
	v_mfma_f32_16x16x32_bf16 v[24:27], v[214:217], v[170:173], v[24:27]
	v_mfma_f32_16x16x32_bf16 v[12:15], v[206:209], v[190:193], v[12:15]
	v_mfma_f32_16x16x32_bf16 v[8:11], v[214:217], v[190:193], v[8:11]
	v_mfma_f32_16x16x32_bf16 v[4:7], v[206:209], v[198:201], v[4:7]
	v_mfma_f32_16x16x32_bf16 v[0:3], v[214:217], v[198:201], v[0:3]
	v_add_u32_e32 v154, 0x18000, v139
	s_barrier
	ds_read_b128 v[142:145], v154
	ds_read_b128 v[146:149], v154 offset:1024
	ds_read_b128 v[150:153], v154 offset:2048
	ds_read_b128 v[154:157], v154 offset:3072
	s_add_u32 s16, s16, 0x40000
	s_addc_u32 s17, s17, 0
	s_mov_b32 m0, s23
	ds_read_b128 v[158:161], v141 offset:32768
	ds_read_b128 v[162:165], v141 offset:33792
	ds_read_b128 v[166:169], v141 offset:34816
	ds_read_b128 v[170:173], v141 offset:35840
	ds_read_b128 v[182:185], v141 offset:36864
	ds_read_b128 v[190:193], v141 offset:37888
	ds_read_b128 v[194:197], v141 offset:38912
	global_load_lds_dwordx4 v132, s[16:17]
	s_mov_b32 m0, s26
	ds_read_b128 v[198:201], v141 offset:39936
	global_load_lds_dwordx4 v130, s[16:17]
	s_waitcnt lgkmcnt(8)
	s_barrier
	s_waitcnt lgkmcnt(7)
	v_mfma_f32_16x16x32_bf16 v[124:127], v[142:145], v[158:161], v[124:127]
	v_mfma_f32_16x16x32_bf16 v[120:123], v[150:153], v[158:161], v[120:123]
	s_waitcnt lgkmcnt(5)
	v_mfma_f32_16x16x32_bf16 v[116:119], v[142:145], v[166:169], v[116:119]
	v_mfma_f32_16x16x32_bf16 v[112:115], v[150:153], v[166:169], v[112:115]
	s_waitcnt lgkmcnt(3)
	v_mfma_f32_16x16x32_bf16 v[100:103], v[142:145], v[182:185], v[100:103]
	v_mfma_f32_16x16x32_bf16 v[96:99], v[150:153], v[182:185], v[96:99]
	s_waitcnt lgkmcnt(1)
	v_mfma_f32_16x16x32_bf16 v[84:87], v[142:145], v[194:197], v[84:87]
	v_mfma_f32_16x16x32_bf16 v[80:83], v[150:153], v[194:197], v[80:83]
	v_mfma_f32_16x16x32_bf16 v[124:127], v[146:149], v[162:165], v[124:127]
	v_mfma_f32_16x16x32_bf16 v[120:123], v[154:157], v[162:165], v[120:123]
	v_mfma_f32_16x16x32_bf16 v[116:119], v[146:149], v[170:173], v[116:119]
	v_mfma_f32_16x16x32_bf16 v[112:115], v[154:157], v[170:173], v[112:115]
	v_mfma_f32_16x16x32_bf16 v[100:103], v[146:149], v[190:193], v[100:103]
	v_mfma_f32_16x16x32_bf16 v[96:99], v[154:157], v[190:193], v[96:99]
	s_waitcnt lgkmcnt(0)
	v_mfma_f32_16x16x32_bf16 v[84:87], v[146:149], v[198:201], v[84:87]
	v_mfma_f32_16x16x32_bf16 v[80:83], v[154:157], v[198:201], v[80:83]
	s_barrier
	v_add_u32_e32 v188, 0x1c000, v139
	s_add_i32 m0, s20, 0x18000
	ds_read_b128 v[202:205], v188
	ds_read_b128 v[206:209], v188 offset:1024
	ds_read_b128 v[210:213], v188 offset:2048
	global_load_lds_dwordx4 v176, s[98:99]
	s_add_i32 m0, s20, 0x1a000
	ds_read_b128 v[214:217], v188 offset:3072
	global_load_lds_dwordx4 v128, s[98:99]
	s_barrier
	s_waitcnt lgkmcnt(3)
	v_mfma_f32_16x16x32_bf16 v[108:111], v[202:205], v[158:161], v[108:111]
	s_waitcnt lgkmcnt(1)
	v_mfma_f32_16x16x32_bf16 v[104:107], v[210:213], v[158:161], v[104:107]
	v_mfma_f32_16x16x32_bf16 v[92:95], v[202:205], v[166:169], v[92:95]
	v_mfma_f32_16x16x32_bf16 v[88:91], v[210:213], v[166:169], v[88:91]
	v_mfma_f32_16x16x32_bf16 v[76:79], v[202:205], v[182:185], v[76:79]
	v_mfma_f32_16x16x32_bf16 v[72:75], v[210:213], v[182:185], v[72:75]
	v_mfma_f32_16x16x32_bf16 v[68:71], v[202:205], v[194:197], v[68:71]
	v_mfma_f32_16x16x32_bf16 v[64:67], v[210:213], v[194:197], v[64:67]
	v_mfma_f32_16x16x32_bf16 v[108:111], v[206:209], v[162:165], v[108:111]
	s_waitcnt lgkmcnt(0)
	v_mfma_f32_16x16x32_bf16 v[104:107], v[214:217], v[162:165], v[104:107]
	v_mfma_f32_16x16x32_bf16 v[92:95], v[206:209], v[170:173], v[92:95]
	v_mfma_f32_16x16x32_bf16 v[88:91], v[214:217], v[170:173], v[88:91]
	v_mfma_f32_16x16x32_bf16 v[76:79], v[206:209], v[190:193], v[76:79]
	v_mfma_f32_16x16x32_bf16 v[72:75], v[214:217], v[190:193], v[72:75]
	v_mfma_f32_16x16x32_bf16 v[68:71], v[206:209], v[198:201], v[68:71]
	v_mfma_f32_16x16x32_bf16 v[64:67], v[214:217], v[198:201], v[64:67]
	s_mov_b32 m0, s28
	s_barrier
	ds_read_b128 v[158:161], v141 offset:49152
	ds_read_b128 v[162:165], v141 offset:50176
	ds_read_b128 v[166:169], v141 offset:51200
	ds_read_b128 v[170:173], v141 offset:52224
	ds_read_b128 v[182:185], v141 offset:53248
	ds_read_b128 v[190:193], v141 offset:54272
	ds_read_b128 v[194:197], v141 offset:55296
	global_load_lds_dwordx4 v132, s[100:101]
	s_mov_b32 m0, s29
	ds_read_b128 v[198:201], v141 offset:56320
	global_load_lds_dwordx4 v130, s[100:101]
	s_barrier
; #define PG8_STAGE(bufoff, gbase, voff) do { _Pragma("unroll") for (int _i = 0; _i < 2; ++_i) \
;         __builtin_amdgcn_global_load_lds((const unsigned*)((const char*)(gbase) + (voff)[_i]), (PG8_LAS unsigned*)(lds + (bufoff) + ldsw + _i * 8192), 16, 0, 0); } while (0)
; #define PG8_MMA(ai, bj, At, Bt) do { __builtin_amdgcn_s_setprio(1); _Pragma("unroll") for (int m = 0; m < 4; ++m) _Pragma("unroll") for (int n = 0; n < 2; ++n) _Pragma("unroll") for (int k = 0; k < 2; ++k) \
;         acc[ai][bj][m][n] = __builtin_amdgcn_mfma_f32_16x16x32_bf16(Bt[n][k], At[m][k], acc[ai][bj][m][n], 0, 0, 0); __builtin_amdgcn_s_setprio(0); } while (0)
; #define PG8_WAIT_V(n) asm volatile("s_waitcnt vmcnt(" #n ")" ::: "memory")
; #define PG8_WAIT_L(n) asm volatile("s_waitcnt lgkmcnt(" #n ")" ::: "memory")
; #define PG8_BAR __builtin_amdgcn_s_barrier()
; #define PG8_SCHED __builtin_amdgcn_sched_barrier(0)
; template <class Epi, class Sched>
; __device__ __forceinline__ void gemm_phase(PG8_LAS unsigned char* lds, const Gemm g, const Sched& S, const Epi& E) {
;     ...
;             PG8_BAR; PG8_WAIT_L(0); PG8_MMA(1, 0, At, B0); PG8_BAR; PG8_SCHED;
;             PG8_STAGE(PG8_SB(1, 1), b3 + hstep, voffB);
;             PG8_WAIT_V(6); PG8_BAR; PG8_MMA(1, 1, At, B1); PG8_BAR;
;         }
	s_waitcnt lgkmcnt(7)
	v_mfma_f32_16x16x32_bf16 v[60:63], v[142:145], v[158:161], v[60:63]
	v_mfma_f32_16x16x32_bf16 v[56:59], v[150:153], v[158:161], v[56:59]
	s_waitcnt lgkmcnt(5)
	v_mfma_f32_16x16x32_bf16 v[52:55], v[142:145], v[166:169], v[52:55]
	v_mfma_f32_16x16x32_bf16 v[48:51], v[150:153], v[166:169], v[48:51]
	s_waitcnt lgkmcnt(3)
	v_mfma_f32_16x16x32_bf16 v[36:39], v[142:145], v[182:185], v[36:39]
	v_mfma_f32_16x16x32_bf16 v[32:35], v[150:153], v[182:185], v[32:35]
	s_waitcnt lgkmcnt(1)
	v_mfma_f32_16x16x32_bf16 v[20:23], v[142:145], v[194:197], v[20:23]
	v_mfma_f32_16x16x32_bf16 v[16:19], v[150:153], v[194:197], v[16:19]
	v_mfma_f32_16x16x32_bf16 v[60:63], v[146:149], v[162:165], v[60:63]
	v_mfma_f32_16x16x32_bf16 v[56:59], v[154:157], v[162:165], v[56:59]
	v_mfma_f32_16x16x32_bf16 v[52:55], v[146:149], v[170:173], v[52:55]
	v_mfma_f32_16x16x32_bf16 v[48:51], v[154:157], v[170:173], v[48:51]
	v_mfma_f32_16x16x32_bf16 v[36:39], v[146:149], v[190:193], v[36:39]
	v_mfma_f32_16x16x32_bf16 v[32:35], v[154:157], v[190:193], v[32:35]
	s_waitcnt lgkmcnt(0)
	v_mfma_f32_16x16x32_bf16 v[20:23], v[146:149], v[198:201], v[20:23]
	v_mfma_f32_16x16x32_bf16 v[16:19], v[154:157], v[198:201], v[16:19]
	s_barrier
	s_add_u32 s14, s14, 0x40080
	s_addc_u32 s15, s15, 0
	s_add_i32 m0, s20, 0x1c000
	s_nop 0
	global_load_lds_dwordx4 v176, s[14:15]
	s_add_i32 m0, s20, 0x1e000
	s_nop 0
	global_load_lds_dwordx4 v128, s[14:15]
	s_waitcnt vmcnt(6)
	s_barrier
	v_mfma_f32_16x16x32_bf16 v[44:47], v[202:205], v[158:161], v[44:47]
	v_mfma_f32_16x16x32_bf16 v[40:43], v[210:213], v[158:161], v[40:43]
	v_mfma_f32_16x16x32_bf16 v[28:31], v[202:205], v[166:169], v[28:31]
	v_mfma_f32_16x16x32_bf16 v[24:27], v[210:213], v[166:169], v[24:27]
	v_mfma_f32_16x16x32_bf16 v[12:15], v[202:205], v[182:185], v[12:15]
	v_mfma_f32_16x16x32_bf16 v[8:11], v[210:213], v[182:185], v[8:11]
	v_mfma_f32_16x16x32_bf16 v[4:7], v[202:205], v[194:197], v[4:7]
	v_mfma_f32_16x16x32_bf16 v[0:3], v[210:213], v[194:197], v[0:3]
	v_mfma_f32_16x16x32_bf16 v[44:47], v[206:209], v[162:165], v[44:47]
	v_mfma_f32_16x16x32_bf16 v[40:43], v[214:217], v[162:165], v[40:43]
	v_mfma_f32_16x16x32_bf16 v[28:31], v[206:209], v[170:173], v[28:31]
	v_mfma_f32_16x16x32_bf16 v[24:27], v[214:217], v[170:173], v[24:27]
	v_mfma_f32_16x16x32_bf16 v[12:15], v[206:209], v[190:193], v[12:15]
	v_mfma_f32_16x16x32_bf16 v[8:11], v[214:217], v[190:193], v[8:11]
	v_mfma_f32_16x16x32_bf16 v[4:7], v[206:209], v[198:201], v[4:7]
	v_mfma_f32_16x16x32_bf16 v[0:3], v[214:217], v[198:201], v[0:3]
	s_add_i32 s45, s45, 2
	s_add_u32 s12, s12, 0x100
	s_addc_u32 s13, s13, 0
	s_add_u32 s43, s43, 0x100
	s_addc_u32 s44, s44, 0
	s_cmp_gt_u32 s45, 13
	s_barrier
	s_cbranch_scc0 .LBB0_358
; __device__ __forceinline__ unsigned cvtpk(float lo, float hi) { const f32x2 v = (f32x2){lo, hi}; const bf16v2 b = __builtin_convertvector(v, bf16v2); return __builtin_bit_cast(unsigned, b); }
; template <class Epi, class Sched>
; __device__ __forceinline__ void gemm_phase(PG8_LAS unsigned char* lds, const Gemm g, const Sched& S, const Epi& E) {
;     ...
;         if constexpr (!Epi::AFTER_DRAIN) { E(acc, cur, wr, wc, fr, fq); S.done(cur); }
;         if (!has_next) break;
; #pragma unroll
;         for (int a = 0; a < 2; ++a)
; #pragma unroll
;             for (int b = 0; b < 2; ++b)
; #pragma unroll
;                 for (int m = 0; m < 4; ++m)
; #pragma unroll
;                     for (int n = 0; n < 2; ++n) acc[a][b][m][n] = (f32x4){0.f, 0.f, 0.f, 0.f};
;         cur = nxt; cA = nA; cB = nB; ++ui;
;     __device__ __forceinline__ void operator()(const f32x4 (&acc)[2][2][4][2], const pg8::Unit& u, int wr, int wc, int fr, int fq) const {
;         const int row0 = u.pm * 256 + wr * 64 + fr, col0 = u.pn * 256 + wc * 32 + 8 * fq;
; #pragma unroll
;         for (int ai = 0; ai < 2; ++ai)
; #pragma unroll
;             for (int m = 0; m < 4; ++m) { bf16_t* rowp = O + (size_t)(row0 + ai * 128 + m * 16) * ldc + col0;
; #pragma unroll
;                 for (int bj = 0; bj < 2; ++bj) { const f32x4 v0 = acc[ai][bj][m][0], v1 = acc[ai][bj][m][1];
;                     u32x4 w; w.x = cvtpk(v0[0], v0[1]); w.y = cvtpk(v0[2], v0[3]); w.z = cvtpk(v1[0], v1[1]); w.w = cvtpk(v1[2], v1[3]);
;                     *(u32x4*)(rowp + bj * 128) = w; } }
;     }
	v_readlane_b32 s12, v253, 16
	v_lshl_add_u32 v148, s0, 8, v138
	v_lshl_or_b32 v142, s34, 8, v140
	v_readlane_b32 s13, v253, 17
	v_ashrrev_i32_e32 v143, 31, v142
	v_cvt_pk_bf16_f32 v68, v68, v69
	v_mov_b64_e32 v[144:145], s[12:13]
	v_cvt_pk_bf16_f32 v69, v70, v71
	v_cvt_pk_bf16_f32 v70, v64, v65
	v_add_u32_e32 v64, 0x80, v148
	v_mad_i64_i32 v[146:147], s[12:13], v148, s81, v[144:145]
	v_lshlrev_b64 v[142:143], 1, v[142:143]
	v_cvt_pk_bf16_f32 v108, v108, v109
	v_cvt_pk_bf16_f32 v109, v110, v111
	v_cvt_pk_bf16_f32 v110, v104, v105
	v_or_b32_e32 v104, 16, v148
	v_mad_i64_i32 v[64:65], s[12:13], v64, s81, v[144:145]
	v_cvt_pk_bf16_f32 v44, v44, v45
	v_cvt_pk_bf16_f32 v45, v46, v47
	v_cvt_pk_bf16_f32 v46, v40, v41
	v_add_u32_e32 v40, 0x90, v148
	v_lshl_add_u64 v[146:147], v[146:147], 0, v[142:143]
	v_cvt_pk_bf16_f32 v111, v106, v107
	v_mad_i64_i32 v[104:105], s[12:13], v104, s81, v[144:145]
	v_cvt_pk_bf16_f32 v92, v92, v93
	v_cvt_pk_bf16_f32 v93, v94, v95
	v_cvt_pk_bf16_f32 v94, v88, v89
	v_or_b32_e32 v88, 32, v148
	v_lshl_add_u64 v[64:65], v[64:65], 0, v[142:143]
	v_cvt_pk_bf16_f32 v47, v42, v43
	v_mad_i64_i32 v[40:41], s[12:13], v40, s81, v[144:145]
	v_cvt_pk_bf16_f32 v28, v28, v29
	v_cvt_pk_bf16_f32 v29, v30, v31
	v_cvt_pk_bf16_f32 v30, v24, v25
	v_add_u32_e32 v24, 0xa0, v148
	global_store_dwordx4 v[146:147], v[108:111], off offset:256
	v_cvt_pk_bf16_f32 v95, v90, v91
	v_mad_i64_i32 v[88:89], s[12:13], v88, s81, v[144:145]
	v_lshl_add_u64 v[108:109], v[104:105], 0, v[142:143]
	v_cvt_pk_bf16_f32 v76, v76, v77
	v_cvt_pk_bf16_f32 v77, v78, v79
	v_cvt_pk_bf16_f32 v78, v72, v73
	v_or_b32_e32 v72, 48, v148
	global_store_dwordx4 v[64:65], v[44:47], off offset:256
	v_cvt_pk_bf16_f32 v31, v26, v27
	v_mad_i64_i32 v[24:25], s[12:13], v24, s81, v[144:145]
	v_lshl_add_u64 v[44:45], v[40:41], 0, v[142:143]
	v_cvt_pk_bf16_f32 v12, v12, v13
	v_cvt_pk_bf16_f32 v13, v14, v15
	v_cvt_pk_bf16_f32 v14, v8, v9
	v_add_u32_e32 v8, 0xb0, v148
	global_store_dwordx4 v[108:109], v[92:95], off offset:256
	v_cvt_pk_bf16_f32 v79, v74, v75
	v_mad_i64_i32 v[72:73], s[12:13], v72, s81, v[144:145]
	v_lshl_add_u64 v[92:93], v[88:89], 0, v[142:143]
	global_store_dwordx4 v[44:45], v[28:31], off offset:256
	v_cvt_pk_bf16_f32 v15, v10, v11
	v_mad_i64_i32 v[8:9], s[12:13], v8, s81, v[144:145]
	v_lshl_add_u64 v[28:29], v[24:25], 0, v[142:143]
	v_cvt_pk_bf16_f32 v124, v124, v125
	v_cvt_pk_bf16_f32 v125, v126, v127
	v_cvt_pk_bf16_f32 v126, v120, v121
	v_cvt_pk_bf16_f32 v127, v122, v123
	v_cvt_pk_bf16_f32 v104, v116, v117
	v_cvt_pk_bf16_f32 v105, v118, v119
	v_cvt_pk_bf16_f32 v106, v112, v113
	v_cvt_pk_bf16_f32 v107, v114, v115
	v_cvt_pk_bf16_f32 v88, v100, v101
	v_cvt_pk_bf16_f32 v89, v102, v103
	v_cvt_pk_bf16_f32 v90, v96, v97
	v_cvt_pk_bf16_f32 v91, v98, v99
	global_store_dwordx4 v[92:93], v[76:79], off offset:256
	v_cvt_pk_bf16_f32 v74, v80, v81
	v_cvt_pk_bf16_f32 v75, v82, v83
	v_lshl_add_u64 v[76:77], v[72:73], 0, v[142:143]
	v_cvt_pk_bf16_f32 v72, v84, v85
	v_cvt_pk_bf16_f32 v73, v86, v87
	v_cvt_pk_bf16_f32 v71, v66, v67
	v_cvt_pk_bf16_f32 v60, v60, v61
	v_cvt_pk_bf16_f32 v61, v62, v63
	v_cvt_pk_bf16_f32 v62, v56, v57
	v_cvt_pk_bf16_f32 v63, v58, v59
	v_cvt_pk_bf16_f32 v40, v52, v53
	v_cvt_pk_bf16_f32 v41, v54, v55
	v_cvt_pk_bf16_f32 v42, v48, v49
	v_cvt_pk_bf16_f32 v43, v50, v51
	v_cvt_pk_bf16_f32 v24, v36, v37
	v_cvt_pk_bf16_f32 v25, v38, v39
	v_cvt_pk_bf16_f32 v26, v32, v33
	v_cvt_pk_bf16_f32 v27, v34, v35
	global_store_dwordx4 v[28:29], v[12:15], off offset:256
	v_cvt_pk_bf16_f32 v10, v16, v17
	v_cvt_pk_bf16_f32 v11, v18, v19
	v_lshl_add_u64 v[12:13], v[8:9], 0, v[142:143]
	v_cvt_pk_bf16_f32 v8, v20, v21
	v_cvt_pk_bf16_f32 v9, v22, v23
	v_cvt_pk_bf16_f32 v4, v4, v5
	v_cvt_pk_bf16_f32 v5, v6, v7
	v_cvt_pk_bf16_f32 v6, v0, v1
	v_cvt_pk_bf16_f32 v7, v2, v3
	s_and_b64 vcc, exec, s[38:39]
	s_mov_b32 s34, s4
	s_mov_b32 s0, s6
	s_mov_b64 s[14:15], s[10:11]
	s_mov_b64 s[12:13], s[8:9]
	global_store_dwordx4 v[146:147], v[124:127], off
	global_store_dwordx4 v[108:109], v[104:107], off
	global_store_dwordx4 v[92:93], v[88:91], off
	global_store_dwordx4 v[76:77], v[72:75], off
	global_store_dwordx4 v[76:77], v[68:71], off offset:256
	global_store_dwordx4 v[64:65], v[60:63], off
	global_store_dwordx4 v[44:45], v[40:43], off
	global_store_dwordx4 v[28:29], v[24:27], off
	global_store_dwordx4 v[12:13], v[8:11], off
	global_store_dwordx4 v[12:13], v[4:7], off offset:256
	s_cbranch_vccz .LBB0_355
	s_waitcnt vmcnt(0)
	v_readlane_b32 s22, v255, 14
	s_cmpk_gt_u32 s19, 0xff
	v_readlane_b32 s23, v255, 15
	s_mov_b64 s[28:29], s[54:55]
	s_cbranch_scc1 .LBB0_362
	s_barrier
